# conv tap loop 2-deep raw-token prefetch (unrolled x2, two register sets) and redundant accumulator re-zeroing removed in GEMM1/pool/out tile loops
# speedup vs baseline: 1.0439x; 1.0103x over previous
; #define PG8_STAGE(bufoff, gbase, voff) do { _Pragma("unroll") for (int _i = 0; _i < 2; ++_i) \
;         __builtin_amdgcn_global_load_lds((const unsigned*)((const char*)(gbase) + (voff)[_i]), (LAS unsigned*)(lds + (bufoff) + ldsw + _i * 8192), 16, 0, 0); } while (0)
; #define PG8_LDA(dst, b, h) do { _Pragma("unroll") for (int m = 0; m < 4; ++m) _Pragma("unroll") for (int k = 0; k < 2; ++k) dst[m][k] = *(const LAS bf16x8*)(lds + PG8_SA(b, h) + aoff + m * 2048 + k * 1024); } while (0)
; #define PG8_LDB(dst, b, h) do { _Pragma("unroll") for (int n = 0; n < 2; ++n) _Pragma("unroll") for (int k = 0; k < 2; ++k) dst[n][k] = *(const LAS bf16x8*)(lds + PG8_SB(b, h) + boff + n * 2048 + k * 1024); } while (0)
; #define PG8_SCHED __builtin_amdgcn_sched_barrier(0)
;     __device__ __forceinline__ bool zero_after(const Unit& u) const { return (u.pm >> 6) == 3; }
; template <bool ALIGN_EPI, bool SP2, class Epi, class Sched>
; __device__ __forceinline__ void gemm_phase(LAS unsigned char* lds, const Gemm g, const Sched& S, const Epi& E) {
;     ...
;         for (int t = 0; t < nt; t += 2) {
;             const bool last = (t == nt - 2);
;             const char* a1 = cA + (size_t)(t + 1) * kstep;
;             const char* a2 = last ? nA : cA + (size_t)(t + 2) * kstep; const char* b2 = last ? nB : cB + (size_t)(t + 2) * kstep;
;             const char* a3 = a2 + kstep; const char* b3 = b2 + kstep;
;             if constexpr (SP2) {
;             PG8_STAGE(PG8_SA(1, 1), a1 + hstep, voffA); PG8_SCHED; PG8_LDB(B0, 0, 0); PG8_LDB(B1, 0, 1); PG8_SCHED; PG8_LDA(At, 0, 0);
;     ...
;         if (E.zero_after(cur))
; #pragma unroll
;         for (int a = 0; a < 2; ++a)
; #pragma unroll
;             for (int b = 0; b < 2; ++b)
; #pragma unroll
;                 for (int m = 0; m < 4; ++m)
; #pragma unroll
;                     for (int n = 0; n < 2; ++n) acc[a][b][m][n] = (f32x4){0.f, 0.f, 0.f, 0.f};
.LBB0_233:
	v_mov_b32_e32 v117, 0
	s_andn2_b64 vcc, exec, s[38:39]
	v_mov_b32_e32 v116, v117
	v_mov_b32_e32 v115, v117
	v_mov_b32_e32 v114, v117
	v_mov_b32_e32 v129, v117
	v_mov_b32_e32 v128, v117
	v_mov_b32_e32 v127, v117
	v_mov_b32_e32 v126, v117
	v_mov_b32_e32 v101, v117
	v_mov_b32_e32 v100, v117
	v_mov_b32_e32 v99, v117
	v_mov_b32_e32 v98, v117
	v_mov_b32_e32 v113, v117
	v_mov_b32_e32 v112, v117
	v_mov_b32_e32 v111, v117
	v_mov_b32_e32 v110, v117
	v_mov_b32_e32 v85, v117
	v_mov_b32_e32 v84, v117
	v_mov_b32_e32 v83, v117
	v_mov_b32_e32 v82, v117
	v_mov_b32_e32 v97, v117
	v_mov_b32_e32 v96, v117
	v_mov_b32_e32 v95, v117
	v_mov_b32_e32 v94, v117
	v_mov_b32_e32 v69, v117
	v_mov_b32_e32 v68, v117
	v_mov_b32_e32 v67, v117
	v_mov_b32_e32 v66, v117
	v_mov_b32_e32 v81, v117
	v_mov_b32_e32 v80, v117
	v_mov_b32_e32 v79, v117
	v_mov_b32_e32 v78, v117
	v_mov_b32_e32 v125, v117
	v_mov_b32_e32 v124, v117
	v_mov_b32_e32 v123, v117
	v_mov_b32_e32 v122, v117
	v_mov_b32_e32 v121, v117
	v_mov_b32_e32 v120, v117
	v_mov_b32_e32 v119, v117
	v_mov_b32_e32 v118, v117
	v_mov_b32_e32 v109, v117
	v_mov_b32_e32 v108, v117
	v_mov_b32_e32 v107, v117
	v_mov_b32_e32 v106, v117
	v_mov_b32_e32 v105, v117
	v_mov_b32_e32 v104, v117
	v_mov_b32_e32 v103, v117
	v_mov_b32_e32 v102, v117
	v_mov_b32_e32 v93, v117
	v_mov_b32_e32 v92, v117
	v_mov_b32_e32 v91, v117
	v_mov_b32_e32 v90, v117
	v_mov_b32_e32 v89, v117
	v_mov_b32_e32 v88, v117
	v_mov_b32_e32 v87, v117
	v_mov_b32_e32 v86, v117
	v_mov_b32_e32 v77, v117
	v_mov_b32_e32 v76, v117
	v_mov_b32_e32 v75, v117
	v_mov_b32_e32 v74, v117
	v_mov_b32_e32 v73, v117
	v_mov_b32_e32 v72, v117
	v_mov_b32_e32 v71, v117
	v_mov_b32_e32 v70, v117
	v_mov_b32_e32 v53, v117
	v_mov_b32_e32 v52, v117
	v_mov_b32_e32 v51, v117
	v_mov_b32_e32 v50, v117
	v_mov_b32_e32 v65, v117
	v_mov_b32_e32 v64, v117
	v_mov_b32_e32 v63, v117
	v_mov_b32_e32 v62, v117
	v_mov_b32_e32 v37, v117
	v_mov_b32_e32 v36, v117
	v_mov_b32_e32 v35, v117
	v_mov_b32_e32 v34, v117
	v_mov_b32_e32 v49, v117
	v_mov_b32_e32 v48, v117
	v_mov_b32_e32 v47, v117
	v_mov_b32_e32 v46, v117
	v_mov_b32_e32 v21, v117
	v_mov_b32_e32 v20, v117
	v_mov_b32_e32 v19, v117
	v_mov_b32_e32 v18, v117
	v_mov_b32_e32 v33, v117
	v_mov_b32_e32 v32, v117
	v_mov_b32_e32 v31, v117
	v_mov_b32_e32 v30, v117
	v_mov_b32_e32 v5, v117
	v_mov_b32_e32 v4, v117
	v_mov_b32_e32 v3, v117
	v_mov_b32_e32 v2, v117
	v_mov_b32_e32 v17, v117
	v_mov_b32_e32 v16, v117
	v_mov_b32_e32 v15, v117
	v_mov_b32_e32 v14, v117
	v_mov_b32_e32 v61, v117
	v_mov_b32_e32 v60, v117
	v_mov_b32_e32 v59, v117
	v_mov_b32_e32 v58, v117
	v_mov_b32_e32 v57, v117
	v_mov_b32_e32 v56, v117
	v_mov_b32_e32 v55, v117
	v_mov_b32_e32 v54, v117
	v_mov_b32_e32 v45, v117
	v_mov_b32_e32 v44, v117
	v_mov_b32_e32 v43, v117
	v_mov_b32_e32 v42, v117
	v_mov_b32_e32 v41, v117
	v_mov_b32_e32 v40, v117
	v_mov_b32_e32 v39, v117
	v_mov_b32_e32 v38, v117
	v_mov_b32_e32 v29, v117
	v_mov_b32_e32 v28, v117
	v_mov_b32_e32 v27, v117
	v_mov_b32_e32 v26, v117
	v_mov_b32_e32 v25, v117
	v_mov_b32_e32 v24, v117
	v_mov_b32_e32 v23, v117
	v_mov_b32_e32 v22, v117
	v_mov_b32_e32 v13, v117
	v_mov_b32_e32 v12, v117
	v_mov_b32_e32 v11, v117
	v_mov_b32_e32 v10, v117
	v_mov_b32_e32 v9, v117
	v_mov_b32_e32 v8, v117
	v_mov_b32_e32 v7, v117
	v_mov_b32_e32 v6, v117
	s_cbranch_vccnz .LBB0_236
	s_add_u32 s42, s90, 0x80
	s_addc_u32 s43, s91, 0
	s_add_u32 s24, s44, 0x100
	v_mov_b32_e32 v6, 0
	s_addc_u32 s71, s45, 0
	s_mov_b32 s44, 0
.LBB0_235:
	s_add_i32 s88, s44, 2
	s_add_u32 s89, s42, 0x80
	s_addc_u32 s45, s43, 0
	s_add_i32 m0, s95, 0xc000
	s_add_i32 s90, s95, 0xe000
	v_lshl_add_u64 v[150:151], s[42:43], 0, v[138:139]
	global_load_lds_dwordx4 v[150:151], off
	v_lshl_add_u64 v[150:151], s[42:43], 0, v[148:149]
	s_mov_b32 m0, s90
	s_cmp_eq_u32 s65, s44
	global_load_lds_dwordx4 v[150:151], off
	s_cselect_b32 s44, s48, s89
	s_cselect_b32 s45, s49, s45
	s_cselect_b32 s91, s87, s71
	s_cselect_b32 s90, s86, s24
	s_add_i32 s89, 0, 0x10000
	v_add_u32_e32 v0, s89, v165
	s_add_i32 s92, 0, 0x14000
	ds_read_b128 v[150:153], v0
	ds_read_b128 v[154:157], v0 offset:1024
	ds_read_b128 v[158:161], v0 offset:2048
	ds_read_b128 v[178:181], v0 offset:3072
	v_add_u32_e32 v0, s92, v165
	ds_read_b128 v[182:185], v0
	ds_read_b128 v[186:189], v0 offset:1024
	ds_read_b128 v[190:193], v0 offset:2048
	ds_read_b128 v[194:197], v0 offset:3072
	ds_read_b128 v[198:201], v176
	ds_read_b128 v[202:205], v176 offset:1024
	ds_read_b128 v[206:209], v176 offset:2048
	ds_read_b128 v[210:213], v176 offset:3072
	ds_read_b128 v[214:217], v176 offset:4096
	ds_read_b128 v[218:221], v176 offset:5120
	ds_read_b128 v[222:225], v176 offset:6144
	ds_read_b128 v[226:229], v176 offset:7168
	s_waitcnt vmcnt(8)
	s_waitcnt lgkmcnt(0)
	s_barrier
; #define PG8_STAGE(bufoff, gbase, voff) do { _Pragma("unroll") for (int _i = 0; _i < 2; ++_i) \
;         __builtin_amdgcn_global_load_lds((const unsigned*)((const char*)(gbase) + (voff)[_i]), (LAS unsigned*)(lds + (bufoff) + ldsw + _i * 8192), 16, 0, 0); } while (0)
; #define PG8_LDA(dst, b, h) do { _Pragma("unroll") for (int m = 0; m < 4; ++m) _Pragma("unroll") for (int k = 0; k < 2; ++k) dst[m][k] = *(const LAS bf16x8*)(lds + PG8_SA(b, h) + aoff + m * 2048 + k * 1024); } while (0)
; #define PG8_MMA(ai, bj, At, Bt) do { __builtin_amdgcn_s_setprio(1); _Pragma("unroll") for (int m = 0; m < 4; ++m) _Pragma("unroll") for (int n = 0; n < 2; ++n) _Pragma("unroll") for (int k = 0; k < 2; ++k) \
;         acc[ai][bj][m][n] = __builtin_amdgcn_mfma_f32_16x16x32_bf16(Bt[n][k], At[m][k], acc[ai][bj][m][n], 0, 0, 0); __builtin_amdgcn_s_setprio(0); } while (0)
; #define PG8_WAIT_V(n) asm volatile("s_waitcnt vmcnt(" #n ")" ::: "memory")
; #define PG8_WAIT_L(n) asm volatile("s_waitcnt lgkmcnt(" #n ")" ::: "memory")
; #define PG8_BAR __builtin_amdgcn_s_barrier()
; #define PG8_SCHED __builtin_amdgcn_sched_barrier(0)
; template <bool ALIGN_EPI, bool SP2, class Epi, class Sched>
; __device__ __forceinline__ void gemm_phase(LAS unsigned char* lds, const Gemm g, const Sched& S, const Epi& E) {
;     ...
;             PG8_WAIT_V(8); PG8_WAIT_L(0); PG8_BAR; PG8_MMA(0, 0, At, B0); PG8_MMA(0, 1, At, B1); PG8_BAR; PG8_SCHED;
;             PG8_STAGE(PG8_SB(0, 0), b2, voffB); PG8_STAGE(PG8_SB(0, 1), b2 + hstep, voffB); PG8_STAGE(PG8_SA(0, 0), a2, voffA); PG8_SCHED; PG8_LDA(At, 0, 1);
;             PG8_WAIT_V(8); PG8_WAIT_L(0); PG8_BAR; PG8_MMA(1, 0, At, B0); PG8_MMA(1, 1, At, B1); PG8_BAR; PG8_SCHED;
	s_setprio 1
	s_waitcnt lgkmcnt(0)
	v_mfma_f32_16x16x32_bf16 v[114:117], v[150:153], v[198:201], v[114:117]
	v_mfma_f32_16x16x32_bf16 v[126:129], v[158:161], v[198:201], v[126:129]
	v_mfma_f32_16x16x32_bf16 v[98:101], v[150:153], v[206:209], v[98:101]
	v_mfma_f32_16x16x32_bf16 v[110:113], v[158:161], v[206:209], v[110:113]
	v_mfma_f32_16x16x32_bf16 v[82:85], v[150:153], v[214:217], v[82:85]
	v_mfma_f32_16x16x32_bf16 v[94:97], v[158:161], v[214:217], v[94:97]
	v_mfma_f32_16x16x32_bf16 v[66:69], v[150:153], v[222:225], v[66:69]
	v_mfma_f32_16x16x32_bf16 v[78:81], v[158:161], v[222:225], v[78:81]
	v_mfma_f32_16x16x32_bf16 v[114:117], v[154:157], v[202:205], v[114:117]
	v_mfma_f32_16x16x32_bf16 v[126:129], v[178:181], v[202:205], v[126:129]
	v_mfma_f32_16x16x32_bf16 v[98:101], v[154:157], v[210:213], v[98:101]
	v_mfma_f32_16x16x32_bf16 v[110:113], v[178:181], v[210:213], v[110:113]
	v_mfma_f32_16x16x32_bf16 v[82:85], v[154:157], v[218:221], v[82:85]
	v_mfma_f32_16x16x32_bf16 v[94:97], v[178:181], v[218:221], v[94:97]
	v_mfma_f32_16x16x32_bf16 v[66:69], v[154:157], v[226:229], v[66:69]
	v_mfma_f32_16x16x32_bf16 v[78:81], v[178:181], v[226:229], v[78:81]
	s_setprio 0
	s_setprio 1
	v_mfma_f32_16x16x32_bf16 v[122:125], v[182:185], v[198:201], v[122:125]
	v_mfma_f32_16x16x32_bf16 v[118:121], v[190:193], v[198:201], v[118:121]
	v_mfma_f32_16x16x32_bf16 v[106:109], v[182:185], v[206:209], v[106:109]
	v_mfma_f32_16x16x32_bf16 v[102:105], v[190:193], v[206:209], v[102:105]
	v_mfma_f32_16x16x32_bf16 v[90:93], v[182:185], v[214:217], v[90:93]
	v_mfma_f32_16x16x32_bf16 v[86:89], v[190:193], v[214:217], v[86:89]
	v_mfma_f32_16x16x32_bf16 v[74:77], v[182:185], v[222:225], v[74:77]
	v_mfma_f32_16x16x32_bf16 v[70:73], v[190:193], v[222:225], v[70:73]
	v_mfma_f32_16x16x32_bf16 v[122:125], v[186:189], v[202:205], v[122:125]
	v_mfma_f32_16x16x32_bf16 v[118:121], v[194:197], v[202:205], v[118:121]
	v_mfma_f32_16x16x32_bf16 v[106:109], v[186:189], v[210:213], v[106:109]
	v_mfma_f32_16x16x32_bf16 v[102:105], v[194:197], v[210:213], v[102:105]
	v_mfma_f32_16x16x32_bf16 v[90:93], v[186:189], v[218:221], v[90:93]
	v_mfma_f32_16x16x32_bf16 v[86:89], v[194:197], v[218:221], v[86:89]
	v_mfma_f32_16x16x32_bf16 v[74:77], v[186:189], v[226:229], v[74:77]
	v_mfma_f32_16x16x32_bf16 v[70:73], v[194:197], v[226:229], v[70:73]
	s_setprio 0
	s_barrier
	s_add_i32 s89, s89, s94
	v_lshl_add_u64 v[162:163], s[90:91], 0, v[132:133]
	s_mov_b32 m0, s89
	v_lshl_add_u64 v[230:231], s[90:91], 0, v[136:137]
	global_load_lds_dwordx4 v[162:163], off
	s_add_i32 m0, s89, 0x2000
	s_add_u32 s90, s90, s14
	s_addc_u32 s91, s91, s15
	s_add_i32 s89, s92, s94
	global_load_lds_dwordx4 v[230:231], off
	v_lshl_add_u64 v[232:233], s[90:91], 0, v[132:133]
	s_mov_b32 m0, s89
	v_lshl_add_u64 v[234:235], s[90:91], 0, v[136:137]
	global_load_lds_dwordx4 v[232:233], off
	s_add_i32 m0, s89, 0x2000
	v_lshl_add_u64 v[236:237], s[44:45], 0, v[130:131]
	global_load_lds_dwordx4 v[234:235], off
	s_mov_b32 m0, s95
	v_lshl_add_u64 v[238:239], s[44:45], 0, v[134:135]
	global_load_lds_dwordx4 v[236:237], off
	s_mov_b32 m0, s96
	s_nop 0
	global_load_lds_dwordx4 v[238:239], off
	ds_read_b128 v[198:201], v176 offset:16384
	ds_read_b128 v[202:205], v176 offset:17408
	ds_read_b128 v[206:209], v176 offset:18432
	ds_read_b128 v[210:213], v176 offset:19456
	ds_read_b128 v[214:217], v176 offset:20480
	ds_read_b128 v[218:221], v176 offset:21504
	ds_read_b128 v[222:225], v176 offset:22528
	ds_read_b128 v[226:229], v176 offset:23552
	s_waitcnt vmcnt(8)
	s_waitcnt lgkmcnt(0)
	s_barrier
	s_setprio 1
	s_waitcnt lgkmcnt(0)
	v_mfma_f32_16x16x32_bf16 v[50:53], v[150:153], v[198:201], v[50:53]
	v_mfma_f32_16x16x32_bf16 v[62:65], v[158:161], v[198:201], v[62:65]
	v_mfma_f32_16x16x32_bf16 v[34:37], v[150:153], v[206:209], v[34:37]
	v_mfma_f32_16x16x32_bf16 v[46:49], v[158:161], v[206:209], v[46:49]
	v_mfma_f32_16x16x32_bf16 v[18:21], v[150:153], v[214:217], v[18:21]
	v_mfma_f32_16x16x32_bf16 v[30:33], v[158:161], v[214:217], v[30:33]
	v_mfma_f32_16x16x32_bf16 v[2:5], v[150:153], v[222:225], v[2:5]
	v_mfma_f32_16x16x32_bf16 v[14:17], v[158:161], v[222:225], v[14:17]
	v_mfma_f32_16x16x32_bf16 v[50:53], v[154:157], v[202:205], v[50:53]
	v_mfma_f32_16x16x32_bf16 v[62:65], v[178:181], v[202:205], v[62:65]
	v_mfma_f32_16x16x32_bf16 v[34:37], v[154:157], v[210:213], v[34:37]
	v_mfma_f32_16x16x32_bf16 v[46:49], v[178:181], v[210:213], v[46:49]
	v_mfma_f32_16x16x32_bf16 v[18:21], v[154:157], v[218:221], v[18:21]
	v_mfma_f32_16x16x32_bf16 v[30:33], v[178:181], v[218:221], v[30:33]
	v_mfma_f32_16x16x32_bf16 v[2:5], v[154:157], v[226:229], v[2:5]
	v_mfma_f32_16x16x32_bf16 v[14:17], v[178:181], v[226:229], v[14:17]
	s_setprio 0
	s_setprio 1
	v_mfma_f32_16x16x32_bf16 v[58:61], v[182:185], v[198:201], v[58:61]
	v_mfma_f32_16x16x32_bf16 v[54:57], v[190:193], v[198:201], v[54:57]
	v_mfma_f32_16x16x32_bf16 v[42:45], v[182:185], v[206:209], v[42:45]
	v_mfma_f32_16x16x32_bf16 v[38:41], v[190:193], v[206:209], v[38:41]
	v_mfma_f32_16x16x32_bf16 v[26:29], v[182:185], v[214:217], v[26:29]
	v_mfma_f32_16x16x32_bf16 v[22:25], v[190:193], v[214:217], v[22:25]
	v_mfma_f32_16x16x32_bf16 v[10:13], v[182:185], v[222:225], v[10:13]
	v_mfma_f32_16x16x32_bf16 v[6:9], v[190:193], v[222:225], v[6:9]
	v_mfma_f32_16x16x32_bf16 v[58:61], v[186:189], v[202:205], v[58:61]
	v_mfma_f32_16x16x32_bf16 v[54:57], v[194:197], v[202:205], v[54:57]
	v_mfma_f32_16x16x32_bf16 v[42:45], v[186:189], v[210:213], v[42:45]
	v_mfma_f32_16x16x32_bf16 v[38:41], v[194:197], v[210:213], v[38:41]
	v_mfma_f32_16x16x32_bf16 v[26:29], v[186:189], v[218:221], v[26:29]
	v_mfma_f32_16x16x32_bf16 v[22:25], v[194:197], v[218:221], v[22:25]
	v_mfma_f32_16x16x32_bf16 v[10:13], v[186:189], v[226:229], v[10:13]
	v_mfma_f32_16x16x32_bf16 v[6:9], v[194:197], v[226:229], v[6:9]
	s_setprio 0
	s_barrier
; #define PG8_STAGE(bufoff, gbase, voff) do { _Pragma("unroll") for (int _i = 0; _i < 2; ++_i) \
;         __builtin_amdgcn_global_load_lds((const unsigned*)((const char*)(gbase) + (voff)[_i]), (LAS unsigned*)(lds + (bufoff) + ldsw + _i * 8192), 16, 0, 0); } while (0)
; #define PG8_LDA(dst, b, h) do { _Pragma("unroll") for (int m = 0; m < 4; ++m) _Pragma("unroll") for (int k = 0; k < 2; ++k) dst[m][k] = *(const LAS bf16x8*)(lds + PG8_SA(b, h) + aoff + m * 2048 + k * 1024); } while (0)
; #define PG8_LDB(dst, b, h) do { _Pragma("unroll") for (int n = 0; n < 2; ++n) _Pragma("unroll") for (int k = 0; k < 2; ++k) dst[n][k] = *(const LAS bf16x8*)(lds + PG8_SB(b, h) + boff + n * 2048 + k * 1024); } while (0)
; #define PG8_MMA(ai, bj, At, Bt) do { __builtin_amdgcn_s_setprio(1); _Pragma("unroll") for (int m = 0; m < 4; ++m) _Pragma("unroll") for (int n = 0; n < 2; ++n) _Pragma("unroll") for (int k = 0; k < 2; ++k) \
;         acc[ai][bj][m][n] = __builtin_amdgcn_mfma_f32_16x16x32_bf16(Bt[n][k], At[m][k], acc[ai][bj][m][n], 0, 0, 0); __builtin_amdgcn_s_setprio(0); } while (0)
; #define PG8_WAIT_V(n) asm volatile("s_waitcnt vmcnt(" #n ")" ::: "memory")
; #define PG8_WAIT_L(n) asm volatile("s_waitcnt lgkmcnt(" #n ")" ::: "memory")
; #define PG8_BAR __builtin_amdgcn_s_barrier()
; #define PG8_SCHED __builtin_amdgcn_sched_barrier(0)
; template <bool ALIGN_EPI, bool SP2, class Epi, class Sched>
; __device__ __forceinline__ void gemm_phase(LAS unsigned char* lds, const Gemm g, const Sched& S, const Epi& E) {
;     ...
;             PG8_STAGE(PG8_SA(0, 1), a2 + hstep, voffA); PG8_SCHED; PG8_LDB(B0, 1, 0); PG8_LDB(B1, 1, 1); PG8_SCHED; PG8_LDA(At, 1, 0);
;             PG8_WAIT_V(8); PG8_WAIT_L(0); PG8_BAR; PG8_MMA(0, 0, At, B0); PG8_MMA(0, 1, At, B1); PG8_BAR; PG8_SCHED;
	s_add_u32 s44, s44, s14
	s_addc_u32 s45, s45, s15
	s_mov_b32 m0, s97
	v_lshl_add_u64 v[150:151], s[44:45], 0, v[130:131]
	global_load_lds_dwordx4 v[150:151], off
	v_lshl_add_u64 v[150:151], s[44:45], 0, v[134:135]
	s_mov_b32 m0, s61
	s_nop 0
	global_load_lds_dwordx4 v[150:151], off
	s_add_i32 s44, 0, 0x18000
	v_add_u32_e32 v0, s44, v165
	s_add_i32 s45, 0, 0x1c000
	ds_read_b128 v[150:153], v0
	ds_read_b128 v[154:157], v0 offset:1024
	ds_read_b128 v[158:161], v0 offset:2048
	ds_read_b128 v[178:181], v0 offset:3072
	v_add_u32_e32 v0, s45, v165
	ds_read_b128 v[182:185], v0
	ds_read_b128 v[186:189], v0 offset:1024
	ds_read_b128 v[190:193], v0 offset:2048
	ds_read_b128 v[194:197], v0 offset:3072
	ds_read_b128 v[198:201], v176 offset:32768
	ds_read_b128 v[202:205], v176 offset:33792
	ds_read_b128 v[206:209], v176 offset:34816
	ds_read_b128 v[210:213], v176 offset:35840
	ds_read_b128 v[214:217], v176 offset:36864
	ds_read_b128 v[218:221], v176 offset:37888
	ds_read_b128 v[222:225], v176 offset:38912
	ds_read_b128 v[226:229], v176 offset:39936
	s_waitcnt vmcnt(8)
	s_waitcnt lgkmcnt(0)
	s_barrier
	s_setprio 1
	s_waitcnt lgkmcnt(0)
	v_mfma_f32_16x16x32_bf16 v[114:117], v[150:153], v[198:201], v[114:117]
	v_mfma_f32_16x16x32_bf16 v[126:129], v[158:161], v[198:201], v[126:129]
	v_mfma_f32_16x16x32_bf16 v[98:101], v[150:153], v[206:209], v[98:101]
	v_mfma_f32_16x16x32_bf16 v[110:113], v[158:161], v[206:209], v[110:113]
	v_mfma_f32_16x16x32_bf16 v[82:85], v[150:153], v[214:217], v[82:85]
	v_mfma_f32_16x16x32_bf16 v[94:97], v[158:161], v[214:217], v[94:97]
	v_mfma_f32_16x16x32_bf16 v[66:69], v[150:153], v[222:225], v[66:69]
	v_mfma_f32_16x16x32_bf16 v[78:81], v[158:161], v[222:225], v[78:81]
	v_mfma_f32_16x16x32_bf16 v[114:117], v[154:157], v[202:205], v[114:117]
	v_mfma_f32_16x16x32_bf16 v[126:129], v[178:181], v[202:205], v[126:129]
	v_mfma_f32_16x16x32_bf16 v[98:101], v[154:157], v[210:213], v[98:101]
	v_mfma_f32_16x16x32_bf16 v[110:113], v[178:181], v[210:213], v[110:113]
	v_mfma_f32_16x16x32_bf16 v[82:85], v[154:157], v[218:221], v[82:85]
	v_mfma_f32_16x16x32_bf16 v[94:97], v[178:181], v[218:221], v[94:97]
	v_mfma_f32_16x16x32_bf16 v[66:69], v[154:157], v[226:229], v[66:69]
	v_mfma_f32_16x16x32_bf16 v[78:81], v[178:181], v[226:229], v[78:81]
	s_setprio 0
	s_setprio 1
	v_mfma_f32_16x16x32_bf16 v[122:125], v[182:185], v[198:201], v[122:125]
	v_mfma_f32_16x16x32_bf16 v[118:121], v[190:193], v[198:201], v[118:121]
	v_mfma_f32_16x16x32_bf16 v[106:109], v[182:185], v[206:209], v[106:109]
	v_mfma_f32_16x16x32_bf16 v[102:105], v[190:193], v[206:209], v[102:105]
	v_mfma_f32_16x16x32_bf16 v[90:93], v[182:185], v[214:217], v[90:93]
	v_mfma_f32_16x16x32_bf16 v[86:89], v[190:193], v[214:217], v[86:89]
	v_mfma_f32_16x16x32_bf16 v[74:77], v[182:185], v[222:225], v[74:77]
	v_mfma_f32_16x16x32_bf16 v[70:73], v[190:193], v[222:225], v[70:73]
	v_mfma_f32_16x16x32_bf16 v[122:125], v[186:189], v[202:205], v[122:125]
	v_mfma_f32_16x16x32_bf16 v[118:121], v[194:197], v[202:205], v[118:121]
	v_mfma_f32_16x16x32_bf16 v[106:109], v[186:189], v[210:213], v[106:109]
	v_mfma_f32_16x16x32_bf16 v[102:105], v[194:197], v[210:213], v[102:105]
	v_mfma_f32_16x16x32_bf16 v[90:93], v[186:189], v[218:221], v[90:93]
	v_mfma_f32_16x16x32_bf16 v[86:89], v[194:197], v[218:221], v[86:89]
	v_mfma_f32_16x16x32_bf16 v[74:77], v[186:189], v[226:229], v[74:77]
	v_mfma_f32_16x16x32_bf16 v[70:73], v[194:197], v[226:229], v[70:73]
	s_setprio 0
	s_barrier
; #define PG8_STAGE(bufoff, gbase, voff) do { _Pragma("unroll") for (int _i = 0; _i < 2; ++_i) \
;         __builtin_amdgcn_global_load_lds((const unsigned*)((const char*)(gbase) + (voff)[_i]), (LAS unsigned*)(lds + (bufoff) + ldsw + _i * 8192), 16, 0, 0); } while (0)
; #define PG8_LDA(dst, b, h) do { _Pragma("unroll") for (int m = 0; m < 4; ++m) _Pragma("unroll") for (int k = 0; k < 2; ++k) dst[m][k] = *(const LAS bf16x8*)(lds + PG8_SA(b, h) + aoff + m * 2048 + k * 1024); } while (0)
; #define PG8_MMA(ai, bj, At, Bt) do { __builtin_amdgcn_s_setprio(1); _Pragma("unroll") for (int m = 0; m < 4; ++m) _Pragma("unroll") for (int n = 0; n < 2; ++n) _Pragma("unroll") for (int k = 0; k < 2; ++k) \
;         acc[ai][bj][m][n] = __builtin_amdgcn_mfma_f32_16x16x32_bf16(Bt[n][k], At[m][k], acc[ai][bj][m][n], 0, 0, 0); __builtin_amdgcn_s_setprio(0); } while (0)
; #define PG8_WAIT_V(n) asm volatile("s_waitcnt vmcnt(" #n ")" ::: "memory")
; #define PG8_WAIT_L(n) asm volatile("s_waitcnt lgkmcnt(" #n ")" ::: "memory")
; #define PG8_BAR __builtin_amdgcn_s_barrier()
; #define PG8_SCHED __builtin_amdgcn_sched_barrier(0)
; template <bool ALIGN_EPI, bool SP2, class Epi, class Sched>
; __device__ __forceinline__ void gemm_phase(LAS unsigned char* lds, const Gemm g, const Sched& S, const Epi& E) {
;     ...
;             PG8_STAGE(PG8_SB(1, 0), b3, voffB); PG8_STAGE(PG8_SB(1, 1), b3 + hstep, voffB); PG8_STAGE(PG8_SA(1, 0), a3, voffA); PG8_SCHED; PG8_LDA(At, 1, 1);
;             PG8_WAIT_V(8); PG8_WAIT_L(0); PG8_BAR; PG8_MMA(1, 0, At, B0); PG8_MMA(1, 1, At, B1); PG8_BAR; PG8_SCHED;
	s_add_i32 s44, s44, s94
	v_lshl_add_u64 v[162:163], v[162:163], 0, s[8:9]
	s_mov_b32 m0, s44
	s_nop 0
	global_load_lds_dwordx4 v[162:163], off
	v_lshl_add_u64 v[162:163], v[230:231], 0, s[8:9]
	s_add_i32 m0, s44, 0x2000
	s_add_i32 s44, s45, s94
	global_load_lds_dwordx4 v[162:163], off
	v_lshl_add_u64 v[162:163], v[232:233], 0, s[8:9]
	s_mov_b32 m0, s44
	s_nop 0
	global_load_lds_dwordx4 v[162:163], off
	v_lshl_add_u64 v[162:163], v[234:235], 0, s[8:9]
	s_add_i32 m0, s44, 0x2000
	s_nop 0
	global_load_lds_dwordx4 v[162:163], off
	v_lshl_add_u64 v[162:163], v[236:237], 0, s[8:9]
	s_mov_b32 m0, s62
	s_nop 0
	global_load_lds_dwordx4 v[162:163], off
	v_lshl_add_u64 v[162:163], v[238:239], 0, s[8:9]
	s_mov_b32 m0, s63
	s_nop 0
	global_load_lds_dwordx4 v[162:163], off
	ds_read_b128 v[198:201], v176 offset:49152
	ds_read_b128 v[202:205], v176 offset:50176
	ds_read_b128 v[206:209], v176 offset:51200
	ds_read_b128 v[210:213], v176 offset:52224
	ds_read_b128 v[214:217], v176 offset:53248
	ds_read_b128 v[218:221], v176 offset:54272
	ds_read_b128 v[222:225], v176 offset:55296
	ds_read_b128 v[226:229], v176 offset:56320
	s_waitcnt vmcnt(8)
	s_waitcnt lgkmcnt(0)
	s_barrier
	s_setprio 1
	s_waitcnt lgkmcnt(0)
	v_mfma_f32_16x16x32_bf16 v[50:53], v[150:153], v[198:201], v[50:53]
	v_mfma_f32_16x16x32_bf16 v[62:65], v[158:161], v[198:201], v[62:65]
	v_mfma_f32_16x16x32_bf16 v[34:37], v[150:153], v[206:209], v[34:37]
	v_mfma_f32_16x16x32_bf16 v[46:49], v[158:161], v[206:209], v[46:49]
	v_mfma_f32_16x16x32_bf16 v[18:21], v[150:153], v[214:217], v[18:21]
	v_mfma_f32_16x16x32_bf16 v[30:33], v[158:161], v[214:217], v[30:33]
	v_mfma_f32_16x16x32_bf16 v[2:5], v[150:153], v[222:225], v[2:5]
	v_mfma_f32_16x16x32_bf16 v[14:17], v[158:161], v[222:225], v[14:17]
	v_mfma_f32_16x16x32_bf16 v[50:53], v[154:157], v[202:205], v[50:53]
	v_mfma_f32_16x16x32_bf16 v[62:65], v[178:181], v[202:205], v[62:65]
	v_mfma_f32_16x16x32_bf16 v[34:37], v[154:157], v[210:213], v[34:37]
	v_mfma_f32_16x16x32_bf16 v[46:49], v[178:181], v[210:213], v[46:49]
	v_mfma_f32_16x16x32_bf16 v[18:21], v[154:157], v[218:221], v[18:21]
	v_mfma_f32_16x16x32_bf16 v[30:33], v[178:181], v[218:221], v[30:33]
	v_mfma_f32_16x16x32_bf16 v[2:5], v[154:157], v[226:229], v[2:5]
	v_mfma_f32_16x16x32_bf16 v[14:17], v[178:181], v[226:229], v[14:17]
	s_setprio 0
	s_setprio 1
	v_mfma_f32_16x16x32_bf16 v[58:61], v[182:185], v[198:201], v[58:61]
	v_mfma_f32_16x16x32_bf16 v[54:57], v[190:193], v[198:201], v[54:57]
	v_mfma_f32_16x16x32_bf16 v[42:45], v[182:185], v[206:209], v[42:45]
	v_mfma_f32_16x16x32_bf16 v[38:41], v[190:193], v[206:209], v[38:41]
	v_mfma_f32_16x16x32_bf16 v[26:29], v[182:185], v[214:217], v[26:29]
	v_mfma_f32_16x16x32_bf16 v[22:25], v[190:193], v[214:217], v[22:25]
	v_mfma_f32_16x16x32_bf16 v[10:13], v[182:185], v[222:225], v[10:13]
	v_mfma_f32_16x16x32_bf16 v[6:9], v[190:193], v[222:225], v[6:9]
	v_mfma_f32_16x16x32_bf16 v[58:61], v[186:189], v[202:205], v[58:61]
	v_mfma_f32_16x16x32_bf16 v[54:57], v[194:197], v[202:205], v[54:57]
	v_mfma_f32_16x16x32_bf16 v[42:45], v[186:189], v[210:213], v[42:45]
	v_mfma_f32_16x16x32_bf16 v[38:41], v[194:197], v[210:213], v[38:41]
	v_mfma_f32_16x16x32_bf16 v[26:29], v[186:189], v[218:221], v[26:29]
	v_mfma_f32_16x16x32_bf16 v[22:25], v[194:197], v[218:221], v[22:25]
	v_mfma_f32_16x16x32_bf16 v[10:13], v[186:189], v[226:229], v[10:13]
	v_mfma_f32_16x16x32_bf16 v[6:9], v[194:197], v[226:229], v[6:9]
	s_setprio 0
	s_barrier
	s_add_u32 s42, s42, 0x100
	s_addc_u32 s43, s43, 0
	s_add_u32 s24, s24, 0x100
	s_addc_u32 s71, s71, 0
	s_cmp_ge_i32 s88, s64
	s_mov_b32 s44, s88
	s_cbranch_scc0 .LBB0_235

; __device__ __forceinline__ float bflo(unsigned w) { return __uint_as_float(w << 16); }
; __device__ __forceinline__ float bfhi(unsigned w) { return __uint_as_float(w & 0xffff0000u); }
; __device__ __forceinline__ void conv_item(KP p, LAS unsigned char* lds, int l, int tile) {
;     ...
;     for (int q = 0; q < 4; ++q) nv[q] = *(const unsigned*)(hm + (size_t)(tbase + q) * HMW + C_GLU);
;     const float* lng = p->in[12] + l * 1024; const float* lnb = p->in[13] + l * 1024;
; #pragma unroll 1
;     for (int hh = 0; hh < 2; ++hh) {
;     const int t0 = tbase + hh * 32;
; #pragma unroll 1
;     for (int blk = 0; blk < 8; ++blk) {
; #pragma unroll
;         for (int q = 0; q < 4; ++q) g[30 + q] = (f32x2){bflo(nv[q]), bfhi(nv[q])};
;         { const int tn = (hh == 1 && blk == 7) ? t0 + blk * 4 : t0 + (blk + 1) * 4;
; #pragma unroll
;           for (int q = 0; q < 4; ++q) nv[q] = *(const unsigned*)(hm + (size_t)(tn + q) * HMW + C_GLU); }
.LBB0_460:
	s_mul_i32 s6, s6, 0x84000
	v_lshl_add_u64 v[4:5], s[6:7], 1, v[82:83]
	v_add_co_u32_e32 v8, vcc, 0x3000, v4
	v_lshl_add_u32 v175, v2, 2, 0
	s_nop 0
	v_addc_co_u32_e32 v9, vcc, 0, v5, vcc
	global_load_dword v174, v[8:9], off offset:512
	v_add_co_u32_e32 v8, vcc, 0x7000, v4
	v_and_b32_e32 v2, 64, v172
	s_nop 0
	v_addc_co_u32_e32 v9, vcc, 0, v5, vcc
	global_load_dword v177, v[8:9], off offset:1024
	v_add_co_u32_e32 v8, vcc, 0xb000, v4
	v_add_u32_e32 v2, 64, v2
	s_nop 0
	v_addc_co_u32_e32 v9, vcc, 0, v5, vcc
	v_add_co_u32_e32 v4, vcc, 0xf000, v4
	global_load_dword v184, v[8:9], off offset:1536
	s_nop 0
	v_addc_co_u32_e32 v5, vcc, 0, v5, vcc
	global_load_dword v185, v[4:5], off offset:2048
	s_mov_b64 s[40:41], 0x4200
	v_lshl_add_u64 v[8:9], v[4:5], 0, s[40:41]
	global_load_dword v236, v[8:9], off offset:2048
	v_lshl_add_u64 v[8:9], v[8:9], 0, s[40:41]
	global_load_dword v237, v[8:9], off offset:2048
	v_lshl_add_u64 v[8:9], v[8:9], 0, s[40:41]
	global_load_dword v238, v[8:9], off offset:2048
	v_lshl_add_u64 v[8:9], v[8:9], 0, s[40:41]
	global_load_dword v239, v[8:9], off offset:2048
	v_xor_b32_e32 v4, 1, v172
	v_cmp_lt_i32_e32 vcc, v4, v2
	s_load_dwordx4 s[40:43], s[0:1], 0x60
	v_and_b32_e32 v3, 63, v6
	v_cndmask_b32_e32 v4, v172, v4, vcc
	v_lshlrev_b32_e32 v176, 2, v4
	v_xor_b32_e32 v4, 2, v172
	v_cmp_lt_i32_e32 vcc, v4, v2
	s_waitcnt lgkmcnt(0)
	s_add_u32 s40, s40, s44
	s_addc_u32 s41, s41, s45
	v_cndmask_b32_e32 v4, v172, v4, vcc
	v_lshlrev_b32_e32 v178, 2, v4
	v_xor_b32_e32 v4, 4, v172
	v_cmp_lt_i32_e32 vcc, v4, v2
	s_add_u32 s42, s42, s44
	s_addc_u32 s43, s43, s45
	v_cndmask_b32_e32 v4, v172, v4, vcc
	v_lshlrev_b32_e32 v179, 2, v4
	v_xor_b32_e32 v4, 8, v172
	v_cmp_lt_i32_e32 vcc, v4, v2
	s_ashr_i32 s6, s24, 4
	s_and_b32 s46, s6, -4
	v_cndmask_b32_e32 v4, v172, v4, vcc
	v_lshlrev_b32_e32 v180, 2, v4
	v_xor_b32_e32 v4, 16, v172
	s_lshl_b32 s6, s6, 12
	v_lshlrev_b32_e32 v0, 4, v3
	v_cmp_lt_i32_e32 vcc, v4, v2
	s_and_b32 s6, s6, 0xffffc000
	v_lshl_add_u64 v[152:153], s[40:41], 0, v[0:1]
	v_cndmask_b32_e32 v4, v172, v4, vcc
	s_add_i32 s6, s6, 0
	v_readlane_b32 s40, v240, 39
	v_lshlrev_b32_e32 v181, 2, v4
	v_xor_b32_e32 v4, 32, v172
	v_lshl_add_u64 v[154:155], s[42:43], 0, v[0:1]
	v_add_u32_e32 v183, s6, v0
	v_lshlrev_b32_e32 v0, 3, v3
	v_readlane_b32 s41, v240, 40
	v_cmp_lt_i32_e32 vcc, v4, v2
	s_lshl_b32 s62, s92, 6
	v_lshl_add_u64 v[156:157], s[40:41], 0, v[0:1]
	v_readlane_b32 s40, v240, 41
	v_cndmask_b32_e32 v2, v172, v4, vcc
	v_readlane_b32 s41, v240, 42
	s_mov_b32 s63, 0
	v_lshlrev_b32_e32 v182, 2, v2
	s_add_i32 s47, s62, 0xffff9004
	s_ashr_i32 s61, s46, 31
	s_addk_i32 s62, 0x9000
	v_lshl_add_u64 v[158:159], s[40:41], 0, v[0:1]
	global_load_dwordx4 v[196:199], v[152:153], off
	global_load_dwordx4 v[200:203], v[154:155], off
	global_load_dwordx4 v[204:207], v[152:153], off offset:1024
	global_load_dwordx4 v[208:211], v[154:155], off offset:1024
	global_load_dwordx4 v[212:215], v[152:153], off offset:2048
	global_load_dwordx4 v[216:219], v[154:155], off offset:2048
	global_load_dwordx4 v[220:223], v[152:153], off offset:3072
	global_load_dwordx4 v[224:227], v[154:155], off offset:3072
	s_mov_b64 s[44:45], -1
	s_mov_b64 s[42:43], 0
.LBB0_461:
	s_or_b32 s6, s63, s25
	s_xor_b64 s[40:41], s[44:45], -1
	s_add_i32 s44, s25, 60
	s_add_i32 s45, s47, s63
	s_mov_b32 s64, 0
.LBB0_462:
	s_add_i32 s6, s45, 4
	s_min_i32 s6, s6, s44
	s_mulk_i32 s6, 0x2100
	v_lshl_add_u64 v[10:11], s[6:7], 1, v[82:83]
	v_add_co_u32_e32 v10, vcc, s52, v10
	s_add_i32 s66, s6, 0x2100
	s_nop 0
	v_addc_co_u32_e32 v11, vcc, 0, v11, vcc
	s_mov_b32 s67, s7
	v_mov_b64_e32 v[6:7], v[88:89]
	v_mov_b64_e32 v[88:89], v[96:97]
	v_mov_b64_e32 v[96:97], v[104:105]
	v_mov_b64_e32 v[104:105], v[112:113]
	v_mov_b64_e32 v[112:113], v[120:121]
	v_mov_b64_e32 v[120:121], v[128:129]
	v_mov_b64_e32 v[128:129], v[136:137]
	s_waitcnt vmcnt(7)
	v_lshlrev_b32_e32 v136, 16, v174
	v_and_b32_e32 v137, 0xffff0000, v174
	global_load_dword v174, v[10:11], off offset:512
	v_lshl_add_u64 v[10:11], s[66:67], 1, v[82:83]
	v_add_co_u32_e32 v10, vcc, s52, v10
	s_add_i32 s66, s6, 0x4200
	s_nop 0
	v_addc_co_u32_e32 v11, vcc, 0, v11, vcc
	v_mov_b64_e32 v[8:9], v[90:91]
	v_mov_b64_e32 v[90:91], v[98:99]
	v_mov_b64_e32 v[98:99], v[106:107]
	v_mov_b64_e32 v[106:107], v[114:115]
	v_mov_b64_e32 v[114:115], v[122:123]
	v_mov_b64_e32 v[122:123], v[130:131]
	v_mov_b64_e32 v[130:131], v[138:139]
	s_waitcnt vmcnt(7)
	v_lshlrev_b32_e32 v138, 16, v177
	v_and_b32_e32 v139, 0xffff0000, v177
	global_load_dword v177, v[10:11], off offset:512
	v_lshl_add_u64 v[10:11], s[66:67], 1, v[82:83]
	v_add_co_u32_e32 v10, vcc, s52, v10
	s_addk_i32 s6, 0x6300
	s_nop 0
	v_addc_co_u32_e32 v11, vcc, 0, v11, vcc
	v_mov_b64_e32 v[2:3], v[84:85]
	v_mov_b64_e32 v[84:85], v[92:93]
	v_mov_b64_e32 v[92:93], v[100:101]
	v_mov_b64_e32 v[100:101], v[108:109]
	v_mov_b64_e32 v[108:109], v[116:117]
	v_mov_b64_e32 v[116:117], v[124:125]
	v_mov_b64_e32 v[124:125], v[132:133]
	v_mov_b64_e32 v[132:133], v[148:149]
	s_waitcnt vmcnt(7)
	v_lshlrev_b32_e32 v148, 16, v184
	v_and_b32_e32 v149, 0xffff0000, v184
	global_load_dword v184, v[10:11], off offset:512
	v_lshl_add_u64 v[10:11], s[6:7], 1, v[82:83]
	v_add_co_u32_e32 v10, vcc, s52, v10
	v_mov_b64_e32 v[4:5], v[86:87]
	s_nop 0
	v_addc_co_u32_e32 v11, vcc, 0, v11, vcc
	v_mov_b64_e32 v[86:87], v[94:95]
	v_mov_b64_e32 v[94:95], v[102:103]
	v_mov_b64_e32 v[102:103], v[110:111]
	v_mov_b64_e32 v[110:111], v[118:119]
	v_mov_b64_e32 v[118:119], v[126:127]
	v_mov_b64_e32 v[126:127], v[134:135]
	v_mov_b64_e32 v[134:135], v[150:151]
	s_waitcnt vmcnt(7)
; __device__ __forceinline__ void conv_item(KP p, LAS unsigned char* lds, int l, int tile) {
;     ...
;         f32x2 y[4] = {cb, cb, cb, cb};
; #pragma unroll
;         for (int j = 0; j < 31; ++j)
; #pragma unroll
;             for (int q = 0; q < 4; ++q) y[q] += w[j] * g[q + j];
	v_lshlrev_b32_e32 v150, 16, v185
	v_and_b32_e32 v151, 0xffff0000, v185
	global_load_dword v185, v[10:11], off offset:512
	v_pk_fma_f32 v[2:3], v[18:19], v[2:3], v[80:81]
	v_pk_fma_f32 v[10:11], v[18:19], v[4:5], v[80:81]
	v_pk_fma_f32 v[12:13], v[18:19], v[6:7], v[80:81]
	v_pk_fma_f32 v[14:15], v[18:19], v[8:9], v[80:81]
	v_pk_fma_f32 v[2:3], v[20:21], v[4:5], v[2:3]
	v_pk_fma_f32 v[4:5], v[20:21], v[6:7], v[10:11]
	v_pk_fma_f32 v[10:11], v[20:21], v[8:9], v[12:13]
	v_pk_fma_f32 v[12:13], v[20:21], v[84:85], v[14:15]
	v_pk_fma_f32 v[2:3], v[22:23], v[6:7], v[2:3]
	v_pk_fma_f32 v[4:5], v[22:23], v[8:9], v[4:5]
	v_pk_fma_f32 v[6:7], v[22:23], v[84:85], v[10:11]
	v_pk_fma_f32 v[10:11], v[22:23], v[86:87], v[12:13]
	v_pk_fma_f32 v[2:3], v[24:25], v[8:9], v[2:3]
	v_pk_fma_f32 v[4:5], v[24:25], v[84:85], v[4:5]
	v_pk_fma_f32 v[6:7], v[24:25], v[86:87], v[6:7]
	v_pk_fma_f32 v[8:9], v[24:25], v[88:89], v[10:11]
	v_pk_fma_f32 v[2:3], v[26:27], v[84:85], v[2:3]
	v_pk_fma_f32 v[4:5], v[26:27], v[86:87], v[4:5]
	v_pk_fma_f32 v[6:7], v[26:27], v[88:89], v[6:7]
	v_pk_fma_f32 v[8:9], v[26:27], v[90:91], v[8:9]
	v_pk_fma_f32 v[2:3], v[28:29], v[86:87], v[2:3]
	v_pk_fma_f32 v[4:5], v[28:29], v[88:89], v[4:5]
	v_pk_fma_f32 v[6:7], v[28:29], v[90:91], v[6:7]
	v_pk_fma_f32 v[8:9], v[28:29], v[92:93], v[8:9]
	v_pk_fma_f32 v[2:3], v[30:31], v[88:89], v[2:3]
	v_pk_fma_f32 v[4:5], v[30:31], v[90:91], v[4:5]
	v_pk_fma_f32 v[6:7], v[30:31], v[92:93], v[6:7]
	v_pk_fma_f32 v[8:9], v[30:31], v[94:95], v[8:9]
	v_pk_fma_f32 v[2:3], v[32:33], v[90:91], v[2:3]
	v_pk_fma_f32 v[4:5], v[32:33], v[92:93], v[4:5]
	v_pk_fma_f32 v[6:7], v[32:33], v[94:95], v[6:7]
	v_pk_fma_f32 v[8:9], v[32:33], v[96:97], v[8:9]
	v_pk_fma_f32 v[2:3], v[34:35], v[92:93], v[2:3]
	v_pk_fma_f32 v[4:5], v[34:35], v[94:95], v[4:5]
	v_pk_fma_f32 v[6:7], v[34:35], v[96:97], v[6:7]
	v_pk_fma_f32 v[8:9], v[34:35], v[98:99], v[8:9]
	v_pk_fma_f32 v[2:3], v[36:37], v[94:95], v[2:3]
	v_pk_fma_f32 v[4:5], v[36:37], v[96:97], v[4:5]
	v_pk_fma_f32 v[6:7], v[36:37], v[98:99], v[6:7]
	v_pk_fma_f32 v[8:9], v[36:37], v[100:101], v[8:9]
	v_pk_fma_f32 v[2:3], v[38:39], v[96:97], v[2:3]
	v_pk_fma_f32 v[4:5], v[38:39], v[98:99], v[4:5]
	v_pk_fma_f32 v[6:7], v[38:39], v[100:101], v[6:7]
	v_pk_fma_f32 v[8:9], v[38:39], v[102:103], v[8:9]
	v_pk_fma_f32 v[2:3], v[40:41], v[98:99], v[2:3]
	v_pk_fma_f32 v[4:5], v[40:41], v[100:101], v[4:5]
	v_pk_fma_f32 v[6:7], v[40:41], v[102:103], v[6:7]
	v_pk_fma_f32 v[8:9], v[40:41], v[104:105], v[8:9]
	v_pk_fma_f32 v[2:3], v[42:43], v[100:101], v[2:3]
	v_pk_fma_f32 v[4:5], v[42:43], v[102:103], v[4:5]
	v_pk_fma_f32 v[6:7], v[42:43], v[104:105], v[6:7]
	v_pk_fma_f32 v[8:9], v[42:43], v[106:107], v[8:9]
	v_pk_fma_f32 v[2:3], v[44:45], v[102:103], v[2:3]
	v_pk_fma_f32 v[4:5], v[44:45], v[104:105], v[4:5]
	v_pk_fma_f32 v[6:7], v[44:45], v[106:107], v[6:7]
	v_pk_fma_f32 v[8:9], v[44:45], v[108:109], v[8:9]
	v_pk_fma_f32 v[2:3], v[46:47], v[104:105], v[2:3]
	v_pk_fma_f32 v[4:5], v[46:47], v[106:107], v[4:5]
	v_pk_fma_f32 v[6:7], v[46:47], v[108:109], v[6:7]
	v_pk_fma_f32 v[8:9], v[46:47], v[110:111], v[8:9]
	v_pk_fma_f32 v[2:3], v[48:49], v[106:107], v[2:3]
	v_pk_fma_f32 v[4:5], v[48:49], v[108:109], v[4:5]
	v_pk_fma_f32 v[6:7], v[48:49], v[110:111], v[6:7]
	v_pk_fma_f32 v[8:9], v[48:49], v[112:113], v[8:9]
	v_pk_fma_f32 v[2:3], v[50:51], v[108:109], v[2:3]
	v_pk_fma_f32 v[4:5], v[50:51], v[110:111], v[4:5]
	v_pk_fma_f32 v[6:7], v[50:51], v[112:113], v[6:7]
	v_pk_fma_f32 v[8:9], v[50:51], v[114:115], v[8:9]
	v_pk_fma_f32 v[2:3], v[52:53], v[110:111], v[2:3]
	v_pk_fma_f32 v[4:5], v[52:53], v[112:113], v[4:5]
	v_pk_fma_f32 v[6:7], v[52:53], v[114:115], v[6:7]
	v_pk_fma_f32 v[8:9], v[52:53], v[116:117], v[8:9]
	v_pk_fma_f32 v[2:3], v[54:55], v[112:113], v[2:3]
	v_pk_fma_f32 v[4:5], v[54:55], v[114:115], v[4:5]
	v_pk_fma_f32 v[6:7], v[54:55], v[116:117], v[6:7]
	v_pk_fma_f32 v[8:9], v[54:55], v[118:119], v[8:9]
	v_pk_fma_f32 v[2:3], v[56:57], v[114:115], v[2:3]
	v_pk_fma_f32 v[4:5], v[56:57], v[116:117], v[4:5]
	v_pk_fma_f32 v[6:7], v[56:57], v[118:119], v[6:7]
	v_pk_fma_f32 v[8:9], v[56:57], v[120:121], v[8:9]
	v_pk_fma_f32 v[2:3], v[58:59], v[116:117], v[2:3]
	v_pk_fma_f32 v[4:5], v[58:59], v[118:119], v[4:5]
	v_pk_fma_f32 v[6:7], v[58:59], v[120:121], v[6:7]
	v_pk_fma_f32 v[8:9], v[58:59], v[122:123], v[8:9]
	v_pk_fma_f32 v[2:3], v[60:61], v[118:119], v[2:3]
	v_pk_fma_f32 v[4:5], v[60:61], v[120:121], v[4:5]
	v_pk_fma_f32 v[6:7], v[60:61], v[122:123], v[6:7]
	v_pk_fma_f32 v[8:9], v[60:61], v[124:125], v[8:9]
	v_pk_fma_f32 v[2:3], v[62:63], v[120:121], v[2:3]
	v_pk_fma_f32 v[4:5], v[62:63], v[122:123], v[4:5]
	v_pk_fma_f32 v[6:7], v[62:63], v[124:125], v[6:7]
	v_pk_fma_f32 v[8:9], v[62:63], v[126:127], v[8:9]
	v_pk_fma_f32 v[2:3], v[64:65], v[122:123], v[2:3]
	v_pk_fma_f32 v[4:5], v[64:65], v[124:125], v[4:5]
	v_pk_fma_f32 v[6:7], v[64:65], v[126:127], v[6:7]
	v_pk_fma_f32 v[8:9], v[64:65], v[128:129], v[8:9]
	v_pk_fma_f32 v[2:3], v[66:67], v[124:125], v[2:3]
	v_pk_fma_f32 v[4:5], v[66:67], v[126:127], v[4:5]
	v_pk_fma_f32 v[6:7], v[66:67], v[128:129], v[6:7]
	v_pk_fma_f32 v[8:9], v[66:67], v[130:131], v[8:9]
	v_pk_fma_f32 v[2:3], v[68:69], v[126:127], v[2:3]
	v_pk_fma_f32 v[4:5], v[68:69], v[128:129], v[4:5]
	v_pk_fma_f32 v[6:7], v[68:69], v[130:131], v[6:7]
	v_pk_fma_f32 v[8:9], v[68:69], v[132:133], v[8:9]
	v_pk_fma_f32 v[2:3], v[70:71], v[128:129], v[2:3]
	v_pk_fma_f32 v[4:5], v[70:71], v[130:131], v[4:5]
	v_pk_fma_f32 v[6:7], v[70:71], v[132:133], v[6:7]
	v_pk_fma_f32 v[8:9], v[70:71], v[134:135], v[8:9]
	v_pk_fma_f32 v[2:3], v[72:73], v[130:131], v[2:3]
	v_pk_fma_f32 v[4:5], v[72:73], v[132:133], v[4:5]
; #define LAS __attribute__((address_space(3)))
; __device__ __forceinline__ float bflo(unsigned w) { return __uint_as_float(w << 16); }
; __device__ __forceinline__ float bfhi(unsigned w) { return __uint_as_float(w & 0xffff0000u); }
; __device__ __forceinline__ void conv_item(KP p, LAS unsigned char* lds, int l, int tile) {
;     ...
;         for (int q = 0; q < 4; ++q) g[30 + q] = (f32x2){bflo(nv[q]), bfhi(nv[q])};
;         { const int tn = (hh == 1 && blk == 7) ? t0 + blk * 4 : t0 + (blk + 1) * 4;
; #pragma unroll
;           for (int q = 0; q < 4; ++q) nv[q] = *(const unsigned*)(hm + (size_t)(tn + q) * HMW + C_GLU); }
;     ...
;             for (int q = 0; q < 4; ++q) y[q] += w[j] * g[q + j];
; #pragma unroll
;         for (int q = 0; q < 4; ++q) *(LAS f32x2*)(ybuf + (blk * 4 + q) * 1024 + c0) = y[q];
; #pragma unroll
;         for (int i = 0; i < 30; ++i) g[i] = g[i + 4];
	v_pk_fma_f32 v[6:7], v[72:73], v[134:135], v[6:7]
	v_pk_fma_f32 v[8:9], v[72:73], v[136:137], v[8:9]
	v_pk_fma_f32 v[2:3], v[74:75], v[132:133], v[2:3]
	v_pk_fma_f32 v[4:5], v[74:75], v[134:135], v[4:5]
	v_pk_fma_f32 v[6:7], v[74:75], v[136:137], v[6:7]
	v_pk_fma_f32 v[8:9], v[74:75], v[138:139], v[8:9]
	v_pk_fma_f32 v[2:3], v[76:77], v[134:135], v[2:3]
	v_pk_fma_f32 v[4:5], v[76:77], v[136:137], v[4:5]
	v_add_u32_e32 v0, s64, v175
	s_add_i32 s45, s45, 4
	s_addk_i32 s64, 0x4000
	v_pk_fma_f32 v[6:7], v[76:77], v[138:139], v[6:7]
	v_pk_fma_f32 v[8:9], v[76:77], v[148:149], v[8:9]
	v_pk_fma_f32 v[2:3], v[78:79], v[136:137], v[2:3]
	v_pk_fma_f32 v[4:5], v[78:79], v[138:139], v[4:5]
	v_pk_fma_f32 v[6:7], v[78:79], v[148:149], v[6:7]
	v_pk_fma_f32 v[8:9], v[78:79], v[150:151], v[8:9]
	ds_write2st64_b64 v0, v[2:3], v[4:5] offset1:8
	ds_write2st64_b64 v0, v[6:7], v[8:9] offset0:16 offset1:24
	s_add_i32 s6, s45, 4
	s_min_i32 s6, s6, s44
	s_mulk_i32 s6, 0x2100
	v_lshl_add_u64 v[10:11], s[6:7], 1, v[82:83]
	v_add_co_u32_e32 v10, vcc, s52, v10
	s_add_i32 s66, s6, 0x2100
	s_nop 0
	v_addc_co_u32_e32 v11, vcc, 0, v11, vcc
	s_mov_b32 s67, s7
	v_mov_b64_e32 v[6:7], v[88:89]
	v_mov_b64_e32 v[88:89], v[96:97]
	v_mov_b64_e32 v[96:97], v[104:105]
	v_mov_b64_e32 v[104:105], v[112:113]
	v_mov_b64_e32 v[112:113], v[120:121]
	v_mov_b64_e32 v[120:121], v[128:129]
	v_mov_b64_e32 v[128:129], v[136:137]
	s_waitcnt vmcnt(7)
	v_lshlrev_b32_e32 v136, 16, v236
	v_and_b32_e32 v137, 0xffff0000, v236
	global_load_dword v236, v[10:11], off offset:512
	v_lshl_add_u64 v[10:11], s[66:67], 1, v[82:83]
	v_add_co_u32_e32 v10, vcc, s52, v10
	s_add_i32 s66, s6, 0x4200
	s_nop 0
	v_addc_co_u32_e32 v11, vcc, 0, v11, vcc
	v_mov_b64_e32 v[8:9], v[90:91]
	v_mov_b64_e32 v[90:91], v[98:99]
	v_mov_b64_e32 v[98:99], v[106:107]
	v_mov_b64_e32 v[106:107], v[114:115]
	v_mov_b64_e32 v[114:115], v[122:123]
	v_mov_b64_e32 v[122:123], v[130:131]
	v_mov_b64_e32 v[130:131], v[138:139]
	s_waitcnt vmcnt(7)
	v_lshlrev_b32_e32 v138, 16, v237
	v_and_b32_e32 v139, 0xffff0000, v237
	global_load_dword v237, v[10:11], off offset:512
	v_lshl_add_u64 v[10:11], s[66:67], 1, v[82:83]
	v_add_co_u32_e32 v10, vcc, s52, v10
	s_addk_i32 s6, 0x6300
	s_nop 0
	v_addc_co_u32_e32 v11, vcc, 0, v11, vcc
	v_mov_b64_e32 v[2:3], v[84:85]
	v_mov_b64_e32 v[84:85], v[92:93]
	v_mov_b64_e32 v[92:93], v[100:101]
	v_mov_b64_e32 v[100:101], v[108:109]
	v_mov_b64_e32 v[108:109], v[116:117]
	v_mov_b64_e32 v[116:117], v[124:125]
	v_mov_b64_e32 v[124:125], v[132:133]
	v_mov_b64_e32 v[132:133], v[148:149]
	s_waitcnt vmcnt(7)
	v_lshlrev_b32_e32 v148, 16, v238
	v_and_b32_e32 v149, 0xffff0000, v238
	global_load_dword v238, v[10:11], off offset:512
	v_lshl_add_u64 v[10:11], s[6:7], 1, v[82:83]
	v_add_co_u32_e32 v10, vcc, s52, v10
	v_mov_b64_e32 v[4:5], v[86:87]
	s_nop 0
	v_addc_co_u32_e32 v11, vcc, 0, v11, vcc
	v_mov_b64_e32 v[86:87], v[94:95]
	v_mov_b64_e32 v[94:95], v[102:103]
	v_mov_b64_e32 v[102:103], v[110:111]
	v_mov_b64_e32 v[110:111], v[118:119]
	v_mov_b64_e32 v[118:119], v[126:127]
	v_mov_b64_e32 v[126:127], v[134:135]
	v_mov_b64_e32 v[134:135], v[150:151]
	s_waitcnt vmcnt(7)
; #define LAS __attribute__((address_space(3)))
; __device__ __forceinline__ float bflo(unsigned w) { return __uint_as_float(w << 16); }
; __device__ __forceinline__ float bfhi(unsigned w) { return __uint_as_float(w & 0xffff0000u); }
; __device__ __forceinline__ void conv_item(KP p, LAS unsigned char* lds, int l, int tile) {
;     ...
;         for (int q = 0; q < 4; ++q) g[30 + q] = (f32x2){bflo(nv[q]), bfhi(nv[q])};
;         { const int tn = (hh == 1 && blk == 7) ? t0 + blk * 4 : t0 + (blk + 1) * 4;
; #pragma unroll
;           for (int q = 0; q < 4; ++q) nv[q] = *(const unsigned*)(hm + (size_t)(tn + q) * HMW + C_GLU); }
;         f32x2 y[4] = {cb, cb, cb, cb};
; #pragma unroll
;         for (int j = 0; j < 31; ++j)
; #pragma unroll
;             for (int q = 0; q < 4; ++q) y[q] += w[j] * g[q + j];
; #pragma unroll
;         for (int q = 0; q < 4; ++q) *(LAS f32x2*)(ybuf + (blk * 4 + q) * 1024 + c0) = y[q];
; #pragma unroll
;         for (int i = 0; i < 30; ++i) g[i] = g[i + 4];
;     }
;     __syncthreads();
	v_lshlrev_b32_e32 v150, 16, v239
	v_and_b32_e32 v151, 0xffff0000, v239
	global_load_dword v239, v[10:11], off offset:512
	v_pk_fma_f32 v[2:3], v[18:19], v[2:3], v[80:81]
	v_pk_fma_f32 v[10:11], v[18:19], v[4:5], v[80:81]
	v_pk_fma_f32 v[12:13], v[18:19], v[6:7], v[80:81]
	v_pk_fma_f32 v[14:15], v[18:19], v[8:9], v[80:81]
	v_pk_fma_f32 v[2:3], v[20:21], v[4:5], v[2:3]
	v_pk_fma_f32 v[4:5], v[20:21], v[6:7], v[10:11]
	v_pk_fma_f32 v[10:11], v[20:21], v[8:9], v[12:13]
	v_pk_fma_f32 v[12:13], v[20:21], v[84:85], v[14:15]
	v_pk_fma_f32 v[2:3], v[22:23], v[6:7], v[2:3]
	v_pk_fma_f32 v[4:5], v[22:23], v[8:9], v[4:5]
	v_pk_fma_f32 v[6:7], v[22:23], v[84:85], v[10:11]
	v_pk_fma_f32 v[10:11], v[22:23], v[86:87], v[12:13]
	v_pk_fma_f32 v[2:3], v[24:25], v[8:9], v[2:3]
	v_pk_fma_f32 v[4:5], v[24:25], v[84:85], v[4:5]
	v_pk_fma_f32 v[6:7], v[24:25], v[86:87], v[6:7]
	v_pk_fma_f32 v[8:9], v[24:25], v[88:89], v[10:11]
	v_pk_fma_f32 v[2:3], v[26:27], v[84:85], v[2:3]
	v_pk_fma_f32 v[4:5], v[26:27], v[86:87], v[4:5]
	v_pk_fma_f32 v[6:7], v[26:27], v[88:89], v[6:7]
	v_pk_fma_f32 v[8:9], v[26:27], v[90:91], v[8:9]
	v_pk_fma_f32 v[2:3], v[28:29], v[86:87], v[2:3]
	v_pk_fma_f32 v[4:5], v[28:29], v[88:89], v[4:5]
	v_pk_fma_f32 v[6:7], v[28:29], v[90:91], v[6:7]
	v_pk_fma_f32 v[8:9], v[28:29], v[92:93], v[8:9]
	v_pk_fma_f32 v[2:3], v[30:31], v[88:89], v[2:3]
	v_pk_fma_f32 v[4:5], v[30:31], v[90:91], v[4:5]
	v_pk_fma_f32 v[6:7], v[30:31], v[92:93], v[6:7]
	v_pk_fma_f32 v[8:9], v[30:31], v[94:95], v[8:9]
	v_pk_fma_f32 v[2:3], v[32:33], v[90:91], v[2:3]
	v_pk_fma_f32 v[4:5], v[32:33], v[92:93], v[4:5]
	v_pk_fma_f32 v[6:7], v[32:33], v[94:95], v[6:7]
	v_pk_fma_f32 v[8:9], v[32:33], v[96:97], v[8:9]
	v_pk_fma_f32 v[2:3], v[34:35], v[92:93], v[2:3]
	v_pk_fma_f32 v[4:5], v[34:35], v[94:95], v[4:5]
	v_pk_fma_f32 v[6:7], v[34:35], v[96:97], v[6:7]
	v_pk_fma_f32 v[8:9], v[34:35], v[98:99], v[8:9]
	v_pk_fma_f32 v[2:3], v[36:37], v[94:95], v[2:3]
	v_pk_fma_f32 v[4:5], v[36:37], v[96:97], v[4:5]
	v_pk_fma_f32 v[6:7], v[36:37], v[98:99], v[6:7]
	v_pk_fma_f32 v[8:9], v[36:37], v[100:101], v[8:9]
	v_pk_fma_f32 v[2:3], v[38:39], v[96:97], v[2:3]
	v_pk_fma_f32 v[4:5], v[38:39], v[98:99], v[4:5]
	v_pk_fma_f32 v[6:7], v[38:39], v[100:101], v[6:7]
	v_pk_fma_f32 v[8:9], v[38:39], v[102:103], v[8:9]
	v_pk_fma_f32 v[2:3], v[40:41], v[98:99], v[2:3]
	v_pk_fma_f32 v[4:5], v[40:41], v[100:101], v[4:5]
	v_pk_fma_f32 v[6:7], v[40:41], v[102:103], v[6:7]
	v_pk_fma_f32 v[8:9], v[40:41], v[104:105], v[8:9]
	v_pk_fma_f32 v[2:3], v[42:43], v[100:101], v[2:3]
	v_pk_fma_f32 v[4:5], v[42:43], v[102:103], v[4:5]
	v_pk_fma_f32 v[6:7], v[42:43], v[104:105], v[6:7]
	v_pk_fma_f32 v[8:9], v[42:43], v[106:107], v[8:9]
	v_pk_fma_f32 v[2:3], v[44:45], v[102:103], v[2:3]
	v_pk_fma_f32 v[4:5], v[44:45], v[104:105], v[4:5]
	v_pk_fma_f32 v[6:7], v[44:45], v[106:107], v[6:7]
	v_pk_fma_f32 v[8:9], v[44:45], v[108:109], v[8:9]
	v_pk_fma_f32 v[2:3], v[46:47], v[104:105], v[2:3]
	v_pk_fma_f32 v[4:5], v[46:47], v[106:107], v[4:5]
	v_pk_fma_f32 v[6:7], v[46:47], v[108:109], v[6:7]
	v_pk_fma_f32 v[8:9], v[46:47], v[110:111], v[8:9]
	v_pk_fma_f32 v[2:3], v[48:49], v[106:107], v[2:3]
	v_pk_fma_f32 v[4:5], v[48:49], v[108:109], v[4:5]
	v_pk_fma_f32 v[6:7], v[48:49], v[110:111], v[6:7]
	v_pk_fma_f32 v[8:9], v[48:49], v[112:113], v[8:9]
	v_pk_fma_f32 v[2:3], v[50:51], v[108:109], v[2:3]
	v_pk_fma_f32 v[4:5], v[50:51], v[110:111], v[4:5]
	v_pk_fma_f32 v[6:7], v[50:51], v[112:113], v[6:7]
	v_pk_fma_f32 v[8:9], v[50:51], v[114:115], v[8:9]
	v_pk_fma_f32 v[2:3], v[52:53], v[110:111], v[2:3]
	v_pk_fma_f32 v[4:5], v[52:53], v[112:113], v[4:5]
	v_pk_fma_f32 v[6:7], v[52:53], v[114:115], v[6:7]
	v_pk_fma_f32 v[8:9], v[52:53], v[116:117], v[8:9]
	v_pk_fma_f32 v[2:3], v[54:55], v[112:113], v[2:3]
	v_pk_fma_f32 v[4:5], v[54:55], v[114:115], v[4:5]
	v_pk_fma_f32 v[6:7], v[54:55], v[116:117], v[6:7]
	v_pk_fma_f32 v[8:9], v[54:55], v[118:119], v[8:9]
	v_pk_fma_f32 v[2:3], v[56:57], v[114:115], v[2:3]
	v_pk_fma_f32 v[4:5], v[56:57], v[116:117], v[4:5]
	v_pk_fma_f32 v[6:7], v[56:57], v[118:119], v[6:7]
	v_pk_fma_f32 v[8:9], v[56:57], v[120:121], v[8:9]
	v_pk_fma_f32 v[2:3], v[58:59], v[116:117], v[2:3]
	v_pk_fma_f32 v[4:5], v[58:59], v[118:119], v[4:5]
	v_pk_fma_f32 v[6:7], v[58:59], v[120:121], v[6:7]
	v_pk_fma_f32 v[8:9], v[58:59], v[122:123], v[8:9]
	v_pk_fma_f32 v[2:3], v[60:61], v[118:119], v[2:3]
	v_pk_fma_f32 v[4:5], v[60:61], v[120:121], v[4:5]
	v_pk_fma_f32 v[6:7], v[60:61], v[122:123], v[6:7]
	v_pk_fma_f32 v[8:9], v[60:61], v[124:125], v[8:9]
	v_pk_fma_f32 v[2:3], v[62:63], v[120:121], v[2:3]
	v_pk_fma_f32 v[4:5], v[62:63], v[122:123], v[4:5]
	v_pk_fma_f32 v[6:7], v[62:63], v[124:125], v[6:7]
	v_pk_fma_f32 v[8:9], v[62:63], v[126:127], v[8:9]
	v_pk_fma_f32 v[2:3], v[64:65], v[122:123], v[2:3]
	v_pk_fma_f32 v[4:5], v[64:65], v[124:125], v[4:5]
	v_pk_fma_f32 v[6:7], v[64:65], v[126:127], v[6:7]
	v_pk_fma_f32 v[8:9], v[64:65], v[128:129], v[8:9]
	v_pk_fma_f32 v[2:3], v[66:67], v[124:125], v[2:3]
	v_pk_fma_f32 v[4:5], v[66:67], v[126:127], v[4:5]
	v_pk_fma_f32 v[6:7], v[66:67], v[128:129], v[6:7]
	v_pk_fma_f32 v[8:9], v[66:67], v[130:131], v[8:9]
	v_pk_fma_f32 v[2:3], v[68:69], v[126:127], v[2:3]
	v_pk_fma_f32 v[4:5], v[68:69], v[128:129], v[4:5]
	v_pk_fma_f32 v[6:7], v[68:69], v[130:131], v[6:7]
	v_pk_fma_f32 v[8:9], v[68:69], v[132:133], v[8:9]
	v_pk_fma_f32 v[2:3], v[70:71], v[128:129], v[2:3]
	v_pk_fma_f32 v[4:5], v[70:71], v[130:131], v[4:5]
	v_pk_fma_f32 v[6:7], v[70:71], v[132:133], v[6:7]
	v_pk_fma_f32 v[8:9], v[70:71], v[134:135], v[8:9]
	v_pk_fma_f32 v[2:3], v[72:73], v[130:131], v[2:3]
	v_pk_fma_f32 v[4:5], v[72:73], v[132:133], v[4:5]
	v_pk_fma_f32 v[6:7], v[72:73], v[134:135], v[6:7]
	v_pk_fma_f32 v[8:9], v[72:73], v[136:137], v[8:9]
	v_pk_fma_f32 v[2:3], v[74:75], v[132:133], v[2:3]
	v_pk_fma_f32 v[4:5], v[74:75], v[134:135], v[4:5]
	v_pk_fma_f32 v[6:7], v[74:75], v[136:137], v[6:7]
	v_pk_fma_f32 v[8:9], v[74:75], v[138:139], v[8:9]
	v_pk_fma_f32 v[2:3], v[76:77], v[134:135], v[2:3]
	v_pk_fma_f32 v[4:5], v[76:77], v[136:137], v[4:5]
	v_add_u32_e32 v0, s64, v175
	s_add_i32 s45, s45, 4
	s_addk_i32 s64, 0x4000
	v_pk_fma_f32 v[6:7], v[76:77], v[138:139], v[6:7]
	v_pk_fma_f32 v[8:9], v[76:77], v[148:149], v[8:9]
	v_pk_fma_f32 v[2:3], v[78:79], v[136:137], v[2:3]
	v_pk_fma_f32 v[4:5], v[78:79], v[138:139], v[4:5]
	s_cmp_lg_u32 s64, 0x20000
	v_pk_fma_f32 v[6:7], v[78:79], v[148:149], v[6:7]
	v_pk_fma_f32 v[8:9], v[78:79], v[150:151], v[8:9]
	ds_write2st64_b64 v0, v[2:3], v[4:5] offset1:8
	ds_write2st64_b64 v0, v[6:7], v[8:9] offset0:16 offset1:24
	s_cbranch_scc1 .LBB0_462
	s_add_i32 s6, s62, s63
	s_add_u32 s42, s46, s6
	s_addc_u32 s43, s61, 0
	s_mul_i32 s6, s43, 0x4200
	v_mad_u64_u32 v[160:161], s[44:45], s42, v171, v[156:157]
	s_lshl_b64 s[42:43], s[42:43], 11
	v_add_u32_e32 v161, s6, v161
	v_lshl_add_u64 v[162:163], v[158:159], 0, s[42:43]
	s_mov_b32 s6, 0
	s_waitcnt lgkmcnt(0)
	s_barrier

; #define PG8_STAGE(bufoff, gbase, voff) do { _Pragma("unroll") for (int _i = 0; _i < 2; ++_i) \
;         __builtin_amdgcn_global_load_lds((const unsigned*)((const char*)(gbase) + (voff)[_i]), (LAS unsigned*)(lds + (bufoff) + ldsw + _i * 8192), 16, 0, 0); } while (0)
; #define PG8_LDA(dst, b, h) do { _Pragma("unroll") for (int m = 0; m < 4; ++m) _Pragma("unroll") for (int k = 0; k < 2; ++k) dst[m][k] = *(const LAS bf16x8*)(lds + PG8_SA(b, h) + aoff + m * 2048 + k * 1024); } while (0)
; #define PG8_LDB(dst, b, h) do { _Pragma("unroll") for (int n = 0; n < 2; ++n) _Pragma("unroll") for (int k = 0; k < 2; ++k) dst[n][k] = *(const LAS bf16x8*)(lds + PG8_SB(b, h) + boff + n * 2048 + k * 1024); } while (0)
; #define PG8_SCHED __builtin_amdgcn_sched_barrier(0)
;     __device__ __forceinline__ bool zero_after(const Unit& u) const { return (u.pm >> 6) == 3; }
; template <bool ALIGN_EPI, bool SP2, class Epi, class Sched>
; __device__ __forceinline__ void gemm_phase(LAS unsigned char* lds, const Gemm g, const Sched& S, const Epi& E) {
;     ...
;         for (int t = 0; t < nt; t += 2) {
;             const bool last = (t == nt - 2);
;             const char* a1 = cA + (size_t)(t + 1) * kstep;
;             const char* a2 = last ? nA : cA + (size_t)(t + 2) * kstep; const char* b2 = last ? nB : cB + (size_t)(t + 2) * kstep;
;             const char* a3 = a2 + kstep; const char* b3 = b2 + kstep;
;             if constexpr (SP2) {
;             PG8_STAGE(PG8_SA(1, 1), a1 + hstep, voffA); PG8_SCHED; PG8_LDB(B0, 0, 0); PG8_LDB(B1, 0, 1); PG8_SCHED; PG8_LDA(At, 0, 0);
;     ...
;         if (E.zero_after(cur))
; #pragma unroll
;         for (int a = 0; a < 2; ++a)
; #pragma unroll
;             for (int b = 0; b < 2; ++b)
; #pragma unroll
;                 for (int m = 0; m < 4; ++m)
; #pragma unroll
;                     for (int n = 0; n < 2; ++n) acc[a][b][m][n] = (f32x4){0.f, 0.f, 0.f, 0.f};
.LBB0_617:
	v_mov_b32_e32 v129, 0
	s_andn2_b64 vcc, exec, s[42:43]
	v_mov_b32_e32 v128, v129
	v_mov_b32_e32 v127, v129
	v_mov_b32_e32 v126, v129
	v_mov_b32_e32 v125, v129
	v_mov_b32_e32 v124, v129
	v_mov_b32_e32 v123, v129
	v_mov_b32_e32 v122, v129
	v_mov_b32_e32 v113, v129
	v_mov_b32_e32 v112, v129
	v_mov_b32_e32 v111, v129
	v_mov_b32_e32 v110, v129
	v_mov_b32_e32 v109, v129
	v_mov_b32_e32 v108, v129
	v_mov_b32_e32 v107, v129
	v_mov_b32_e32 v106, v129
	v_mov_b32_e32 v97, v129
	v_mov_b32_e32 v96, v129
	v_mov_b32_e32 v95, v129
	v_mov_b32_e32 v94, v129
	v_mov_b32_e32 v93, v129
	v_mov_b32_e32 v92, v129
	v_mov_b32_e32 v91, v129
	v_mov_b32_e32 v90, v129
	v_mov_b32_e32 v81, v129
	v_mov_b32_e32 v80, v129
	v_mov_b32_e32 v79, v129
	v_mov_b32_e32 v78, v129
	v_mov_b32_e32 v77, v129
	v_mov_b32_e32 v76, v129
	v_mov_b32_e32 v75, v129
	v_mov_b32_e32 v74, v129
	v_mov_b32_e32 v121, v129
	v_mov_b32_e32 v120, v129
	v_mov_b32_e32 v119, v129
	v_mov_b32_e32 v118, v129
	v_mov_b32_e32 v117, v129
	v_mov_b32_e32 v116, v129
	v_mov_b32_e32 v115, v129
	v_mov_b32_e32 v114, v129
	v_mov_b32_e32 v105, v129
	v_mov_b32_e32 v104, v129
	v_mov_b32_e32 v103, v129
	v_mov_b32_e32 v102, v129
	v_mov_b32_e32 v101, v129
	v_mov_b32_e32 v100, v129
	v_mov_b32_e32 v99, v129
	v_mov_b32_e32 v98, v129
	v_mov_b32_e32 v89, v129
	v_mov_b32_e32 v88, v129
	v_mov_b32_e32 v87, v129
	v_mov_b32_e32 v86, v129
	v_mov_b32_e32 v85, v129
	v_mov_b32_e32 v84, v129
	v_mov_b32_e32 v83, v129
	v_mov_b32_e32 v82, v129
	v_mov_b32_e32 v73, v129
	v_mov_b32_e32 v72, v129
	v_mov_b32_e32 v71, v129
	v_mov_b32_e32 v70, v129
	v_mov_b32_e32 v69, v129
	v_mov_b32_e32 v68, v129
	v_mov_b32_e32 v67, v129
	v_mov_b32_e32 v66, v129
	v_mov_b32_e32 v65, v129
	v_mov_b32_e32 v64, v129
	v_mov_b32_e32 v63, v129
	v_mov_b32_e32 v62, v129
	v_mov_b32_e32 v61, v129
	v_mov_b32_e32 v60, v129
	v_mov_b32_e32 v59, v129
	v_mov_b32_e32 v58, v129
	v_mov_b32_e32 v49, v129
	v_mov_b32_e32 v48, v129
	v_mov_b32_e32 v47, v129
	v_mov_b32_e32 v46, v129
	v_mov_b32_e32 v45, v129
	v_mov_b32_e32 v44, v129
	v_mov_b32_e32 v43, v129
	v_mov_b32_e32 v42, v129
	v_mov_b32_e32 v33, v129
	v_mov_b32_e32 v32, v129
	v_mov_b32_e32 v31, v129
	v_mov_b32_e32 v30, v129
	v_mov_b32_e32 v29, v129
	v_mov_b32_e32 v28, v129
	v_mov_b32_e32 v27, v129
	v_mov_b32_e32 v26, v129
	v_mov_b32_e32 v17, v129
	v_mov_b32_e32 v16, v129
	v_mov_b32_e32 v15, v129
	v_mov_b32_e32 v14, v129
	v_mov_b32_e32 v13, v129
	v_mov_b32_e32 v12, v129
	v_mov_b32_e32 v11, v129
	v_mov_b32_e32 v10, v129
	v_mov_b32_e32 v57, v129
	v_mov_b32_e32 v56, v129
	v_mov_b32_e32 v55, v129
	v_mov_b32_e32 v54, v129
	v_mov_b32_e32 v53, v129
	v_mov_b32_e32 v52, v129
	v_mov_b32_e32 v51, v129
	v_mov_b32_e32 v50, v129
	v_mov_b32_e32 v41, v129
	v_mov_b32_e32 v40, v129
	v_mov_b32_e32 v39, v129
	v_mov_b32_e32 v38, v129
	v_mov_b32_e32 v37, v129
	v_mov_b32_e32 v36, v129
	v_mov_b32_e32 v35, v129
	v_mov_b32_e32 v34, v129
	v_mov_b32_e32 v25, v129
	v_mov_b32_e32 v24, v129
	v_mov_b32_e32 v23, v129
	v_mov_b32_e32 v22, v129
	v_mov_b32_e32 v21, v129
	v_mov_b32_e32 v20, v129
	v_mov_b32_e32 v19, v129
	v_mov_b32_e32 v18, v129
	v_mov_b32_e32 v9, v129
	v_mov_b32_e32 v8, v129
	v_mov_b32_e32 v7, v129
	v_mov_b32_e32 v6, v129
	v_mov_b32_e32 v5, v129
	v_mov_b32_e32 v4, v129
	v_mov_b32_e32 v3, v129
	v_mov_b32_e32 v2, v129
	s_cbranch_vccnz .LBB0_621
	s_add_u32 s86, s86, 0x80
	s_addc_u32 s87, s87, 0
	s_add_u32 s24, s90, 0x100
	v_mov_b32_e32 v2, 0
	s_addc_u32 s71, s91, 0
	s_mov_b32 s88, 0
.LBB0_619:
	s_add_i32 s90, s88, 2
	s_add_u32 s91, s86, 0x80
	s_addc_u32 s89, s87, 0
	s_add_i32 m0, s62, 0xc000
	s_add_i32 s94, s62, 0xe000
	v_lshl_add_u64 v[148:149], s[86:87], 0, v[136:137]
	global_load_lds_dwordx4 v[148:149], off
	v_lshl_add_u64 v[148:149], s[86:87], 0, v[138:139]
	s_mov_b32 m0, s94
	s_cmp_eq_u32 s69, s88
	global_load_lds_dwordx4 v[148:149], off
	s_cselect_b32 s88, s46, s91
	s_cselect_b32 s89, s47, s89
	s_cselect_b32 s95, s49, s71
	s_cselect_b32 s94, s48, s24
	s_add_i32 s91, 0, 0x10000
	v_add_u32_e32 v152, s91, v155
	s_add_i32 s96, 0, 0x14000
	ds_read_b128 v[148:151], v152
	ds_read_b128 v[158:161], v152 offset:1024
	ds_read_b128 v[162:165], v152 offset:2048
	ds_read_b128 v[174:177], v152 offset:3072
	v_add_u32_e32 v152, s96, v155
	ds_read_b128 v[178:181], v152
	ds_read_b128 v[182:185], v152 offset:1024
	ds_read_b128 v[186:189], v152 offset:2048
	ds_read_b128 v[190:193], v152 offset:3072
	ds_read_b128 v[194:197], v157
	ds_read_b128 v[198:201], v157 offset:1024
	ds_read_b128 v[202:205], v157 offset:2048
	ds_read_b128 v[206:209], v157 offset:3072
	ds_read_b128 v[210:213], v157 offset:4096
	ds_read_b128 v[214:217], v157 offset:5120
	ds_read_b128 v[218:221], v157 offset:6144
	ds_read_b128 v[222:225], v157 offset:7168
	s_waitcnt vmcnt(8)
	s_waitcnt lgkmcnt(0)
	s_barrier
; #define PG8_STAGE(bufoff, gbase, voff) do { _Pragma("unroll") for (int _i = 0; _i < 2; ++_i) \
;         __builtin_amdgcn_global_load_lds((const unsigned*)((const char*)(gbase) + (voff)[_i]), (LAS unsigned*)(lds + (bufoff) + ldsw + _i * 8192), 16, 0, 0); } while (0)
; #define PG8_LDA(dst, b, h) do { _Pragma("unroll") for (int m = 0; m < 4; ++m) _Pragma("unroll") for (int k = 0; k < 2; ++k) dst[m][k] = *(const LAS bf16x8*)(lds + PG8_SA(b, h) + aoff + m * 2048 + k * 1024); } while (0)
; #define PG8_MMA(ai, bj, At, Bt) do { __builtin_amdgcn_s_setprio(1); _Pragma("unroll") for (int m = 0; m < 4; ++m) _Pragma("unroll") for (int n = 0; n < 2; ++n) _Pragma("unroll") for (int k = 0; k < 2; ++k) \
;         acc[ai][bj][m][n] = __builtin_amdgcn_mfma_f32_16x16x32_bf16(Bt[n][k], At[m][k], acc[ai][bj][m][n], 0, 0, 0); __builtin_amdgcn_s_setprio(0); } while (0)
; #define PG8_WAIT_V(n) asm volatile("s_waitcnt vmcnt(" #n ")" ::: "memory")
; #define PG8_WAIT_L(n) asm volatile("s_waitcnt lgkmcnt(" #n ")" ::: "memory")
; #define PG8_BAR __builtin_amdgcn_s_barrier()
; #define PG8_SCHED __builtin_amdgcn_sched_barrier(0)
; template <bool ALIGN_EPI, bool SP2, class Epi, class Sched>
; __device__ __forceinline__ void gemm_phase(LAS unsigned char* lds, const Gemm g, const Sched& S, const Epi& E) {
;     ...
;             PG8_WAIT_V(8); PG8_WAIT_L(0); PG8_BAR; PG8_MMA(0, 0, At, B0); PG8_MMA(0, 1, At, B1); PG8_BAR; PG8_SCHED;
;             PG8_STAGE(PG8_SB(0, 0), b2, voffB); PG8_STAGE(PG8_SB(0, 1), b2 + hstep, voffB); PG8_STAGE(PG8_SA(0, 0), a2, voffA); PG8_SCHED; PG8_LDA(At, 0, 1);
;             PG8_WAIT_V(8); PG8_WAIT_L(0); PG8_BAR; PG8_MMA(1, 0, At, B0); PG8_MMA(1, 1, At, B1); PG8_BAR; PG8_SCHED;
	s_setprio 1
	s_waitcnt lgkmcnt(0)
	v_mfma_f32_16x16x32_bf16 v[126:129], v[148:151], v[194:197], v[126:129]
	v_mfma_f32_16x16x32_bf16 v[122:125], v[162:165], v[194:197], v[122:125]
	v_mfma_f32_16x16x32_bf16 v[110:113], v[148:151], v[202:205], v[110:113]
	v_mfma_f32_16x16x32_bf16 v[106:109], v[162:165], v[202:205], v[106:109]
	v_mfma_f32_16x16x32_bf16 v[94:97], v[148:151], v[210:213], v[94:97]
	v_mfma_f32_16x16x32_bf16 v[90:93], v[162:165], v[210:213], v[90:93]
	v_mfma_f32_16x16x32_bf16 v[78:81], v[148:151], v[218:221], v[78:81]
	v_mfma_f32_16x16x32_bf16 v[74:77], v[162:165], v[218:221], v[74:77]
	v_mfma_f32_16x16x32_bf16 v[126:129], v[158:161], v[198:201], v[126:129]
	v_mfma_f32_16x16x32_bf16 v[122:125], v[174:177], v[198:201], v[122:125]
	v_mfma_f32_16x16x32_bf16 v[110:113], v[158:161], v[206:209], v[110:113]
	v_mfma_f32_16x16x32_bf16 v[106:109], v[174:177], v[206:209], v[106:109]
	v_mfma_f32_16x16x32_bf16 v[94:97], v[158:161], v[214:217], v[94:97]
	v_mfma_f32_16x16x32_bf16 v[90:93], v[174:177], v[214:217], v[90:93]
	v_mfma_f32_16x16x32_bf16 v[78:81], v[158:161], v[222:225], v[78:81]
	v_mfma_f32_16x16x32_bf16 v[74:77], v[174:177], v[222:225], v[74:77]
	s_setprio 0
	s_setprio 1
	v_mfma_f32_16x16x32_bf16 v[118:121], v[178:181], v[194:197], v[118:121]
	v_mfma_f32_16x16x32_bf16 v[114:117], v[186:189], v[194:197], v[114:117]
	v_mfma_f32_16x16x32_bf16 v[102:105], v[178:181], v[202:205], v[102:105]
	v_mfma_f32_16x16x32_bf16 v[98:101], v[186:189], v[202:205], v[98:101]
	v_mfma_f32_16x16x32_bf16 v[86:89], v[178:181], v[210:213], v[86:89]
	v_mfma_f32_16x16x32_bf16 v[82:85], v[186:189], v[210:213], v[82:85]
	v_mfma_f32_16x16x32_bf16 v[70:73], v[178:181], v[218:221], v[70:73]
	v_mfma_f32_16x16x32_bf16 v[66:69], v[186:189], v[218:221], v[66:69]
	v_mfma_f32_16x16x32_bf16 v[118:121], v[182:185], v[198:201], v[118:121]
	v_mfma_f32_16x16x32_bf16 v[114:117], v[190:193], v[198:201], v[114:117]
	v_mfma_f32_16x16x32_bf16 v[102:105], v[182:185], v[206:209], v[102:105]
	v_mfma_f32_16x16x32_bf16 v[98:101], v[190:193], v[206:209], v[98:101]
	v_mfma_f32_16x16x32_bf16 v[86:89], v[182:185], v[214:217], v[86:89]
	v_mfma_f32_16x16x32_bf16 v[82:85], v[190:193], v[214:217], v[82:85]
	v_mfma_f32_16x16x32_bf16 v[70:73], v[182:185], v[222:225], v[70:73]
	v_mfma_f32_16x16x32_bf16 v[66:69], v[190:193], v[222:225], v[66:69]
	s_setprio 0
	s_barrier
	s_add_i32 s91, s91, s61
	v_lshl_add_u64 v[152:153], s[94:95], 0, v[0:1]
	s_mov_b32 m0, s91
	v_lshl_add_u64 v[226:227], s[94:95], 0, v[130:131]
	global_load_lds_dwordx4 v[152:153], off
	s_add_i32 m0, s91, 0x2000
	s_add_u32 s94, s94, s14
	s_addc_u32 s95, s95, s15
	s_add_i32 s91, s96, s61
	global_load_lds_dwordx4 v[226:227], off
	v_lshl_add_u64 v[228:229], s[94:95], 0, v[0:1]
	s_mov_b32 m0, s91
	v_lshl_add_u64 v[230:231], s[94:95], 0, v[130:131]
	global_load_lds_dwordx4 v[228:229], off
	s_add_i32 m0, s91, 0x2000
	v_lshl_add_u64 v[232:233], s[88:89], 0, v[134:135]
	global_load_lds_dwordx4 v[230:231], off
	s_mov_b32 m0, s62
	v_lshl_add_u64 v[234:235], s[88:89], 0, v[132:133]
	global_load_lds_dwordx4 v[232:233], off
	s_mov_b32 m0, s63
	s_nop 0
	global_load_lds_dwordx4 v[234:235], off
	ds_read_b128 v[194:197], v157 offset:16384
	ds_read_b128 v[198:201], v157 offset:17408
	ds_read_b128 v[202:205], v157 offset:18432
	ds_read_b128 v[206:209], v157 offset:19456
	ds_read_b128 v[210:213], v157 offset:20480
	ds_read_b128 v[214:217], v157 offset:21504
	ds_read_b128 v[218:221], v157 offset:22528
	ds_read_b128 v[222:225], v157 offset:23552
	s_waitcnt vmcnt(8)
	s_waitcnt lgkmcnt(0)
	s_barrier
	s_setprio 1
	s_waitcnt lgkmcnt(0)
	v_mfma_f32_16x16x32_bf16 v[62:65], v[148:151], v[194:197], v[62:65]
	v_mfma_f32_16x16x32_bf16 v[58:61], v[162:165], v[194:197], v[58:61]
	v_mfma_f32_16x16x32_bf16 v[46:49], v[148:151], v[202:205], v[46:49]
	v_mfma_f32_16x16x32_bf16 v[42:45], v[162:165], v[202:205], v[42:45]
	v_mfma_f32_16x16x32_bf16 v[30:33], v[148:151], v[210:213], v[30:33]
	v_mfma_f32_16x16x32_bf16 v[26:29], v[162:165], v[210:213], v[26:29]
	v_mfma_f32_16x16x32_bf16 v[14:17], v[148:151], v[218:221], v[14:17]
	v_mfma_f32_16x16x32_bf16 v[10:13], v[162:165], v[218:221], v[10:13]
	v_mfma_f32_16x16x32_bf16 v[62:65], v[158:161], v[198:201], v[62:65]
	v_mfma_f32_16x16x32_bf16 v[58:61], v[174:177], v[198:201], v[58:61]
	v_mfma_f32_16x16x32_bf16 v[46:49], v[158:161], v[206:209], v[46:49]
	v_mfma_f32_16x16x32_bf16 v[42:45], v[174:177], v[206:209], v[42:45]
	v_mfma_f32_16x16x32_bf16 v[30:33], v[158:161], v[214:217], v[30:33]
	v_mfma_f32_16x16x32_bf16 v[26:29], v[174:177], v[214:217], v[26:29]
	v_mfma_f32_16x16x32_bf16 v[14:17], v[158:161], v[222:225], v[14:17]
	v_mfma_f32_16x16x32_bf16 v[10:13], v[174:177], v[222:225], v[10:13]
	s_setprio 0
	s_setprio 1
	v_mfma_f32_16x16x32_bf16 v[54:57], v[178:181], v[194:197], v[54:57]
	v_mfma_f32_16x16x32_bf16 v[50:53], v[186:189], v[194:197], v[50:53]
	v_mfma_f32_16x16x32_bf16 v[38:41], v[178:181], v[202:205], v[38:41]
	v_mfma_f32_16x16x32_bf16 v[34:37], v[186:189], v[202:205], v[34:37]
	v_mfma_f32_16x16x32_bf16 v[22:25], v[178:181], v[210:213], v[22:25]
	v_mfma_f32_16x16x32_bf16 v[18:21], v[186:189], v[210:213], v[18:21]
	v_mfma_f32_16x16x32_bf16 v[6:9], v[178:181], v[218:221], v[6:9]
	v_mfma_f32_16x16x32_bf16 v[2:5], v[186:189], v[218:221], v[2:5]
	v_mfma_f32_16x16x32_bf16 v[54:57], v[182:185], v[198:201], v[54:57]
	v_mfma_f32_16x16x32_bf16 v[50:53], v[190:193], v[198:201], v[50:53]
	v_mfma_f32_16x16x32_bf16 v[38:41], v[182:185], v[206:209], v[38:41]
	v_mfma_f32_16x16x32_bf16 v[34:37], v[190:193], v[206:209], v[34:37]
	v_mfma_f32_16x16x32_bf16 v[22:25], v[182:185], v[214:217], v[22:25]
	v_mfma_f32_16x16x32_bf16 v[18:21], v[190:193], v[214:217], v[18:21]
	v_mfma_f32_16x16x32_bf16 v[6:9], v[182:185], v[222:225], v[6:9]
	v_mfma_f32_16x16x32_bf16 v[2:5], v[190:193], v[222:225], v[2:5]
	s_setprio 0
	s_barrier
; #define PG8_STAGE(bufoff, gbase, voff) do { _Pragma("unroll") for (int _i = 0; _i < 2; ++_i) \
;         __builtin_amdgcn_global_load_lds((const unsigned*)((const char*)(gbase) + (voff)[_i]), (LAS unsigned*)(lds + (bufoff) + ldsw + _i * 8192), 16, 0, 0); } while (0)
; #define PG8_LDA(dst, b, h) do { _Pragma("unroll") for (int m = 0; m < 4; ++m) _Pragma("unroll") for (int k = 0; k < 2; ++k) dst[m][k] = *(const LAS bf16x8*)(lds + PG8_SA(b, h) + aoff + m * 2048 + k * 1024); } while (0)
; #define PG8_LDB(dst, b, h) do { _Pragma("unroll") for (int n = 0; n < 2; ++n) _Pragma("unroll") for (int k = 0; k < 2; ++k) dst[n][k] = *(const LAS bf16x8*)(lds + PG8_SB(b, h) + boff + n * 2048 + k * 1024); } while (0)
; #define PG8_MMA(ai, bj, At, Bt) do { __builtin_amdgcn_s_setprio(1); _Pragma("unroll") for (int m = 0; m < 4; ++m) _Pragma("unroll") for (int n = 0; n < 2; ++n) _Pragma("unroll") for (int k = 0; k < 2; ++k) \
;         acc[ai][bj][m][n] = __builtin_amdgcn_mfma_f32_16x16x32_bf16(Bt[n][k], At[m][k], acc[ai][bj][m][n], 0, 0, 0); __builtin_amdgcn_s_setprio(0); } while (0)
; #define PG8_WAIT_V(n) asm volatile("s_waitcnt vmcnt(" #n ")" ::: "memory")
; #define PG8_WAIT_L(n) asm volatile("s_waitcnt lgkmcnt(" #n ")" ::: "memory")
; #define PG8_BAR __builtin_amdgcn_s_barrier()
; #define PG8_SCHED __builtin_amdgcn_sched_barrier(0)
; template <bool ALIGN_EPI, bool SP2, class Epi, class Sched>
; __device__ __forceinline__ void gemm_phase(LAS unsigned char* lds, const Gemm g, const Sched& S, const Epi& E) {
;     ...
;             PG8_STAGE(PG8_SA(0, 1), a2 + hstep, voffA); PG8_SCHED; PG8_LDB(B0, 1, 0); PG8_LDB(B1, 1, 1); PG8_SCHED; PG8_LDA(At, 1, 0);
;             PG8_WAIT_V(8); PG8_WAIT_L(0); PG8_BAR; PG8_MMA(0, 0, At, B0); PG8_MMA(0, 1, At, B1); PG8_BAR; PG8_SCHED;
	s_add_u32 s88, s88, s14
	s_addc_u32 s89, s89, s15
	s_mov_b32 m0, s64
	v_lshl_add_u64 v[148:149], s[88:89], 0, v[134:135]
	global_load_lds_dwordx4 v[148:149], off
	v_lshl_add_u64 v[148:149], s[88:89], 0, v[132:133]
	s_mov_b32 m0, s65
	s_nop 0
	global_load_lds_dwordx4 v[148:149], off
	s_add_i32 s88, 0, 0x18000
	s_add_i32 s89, 0, 0x1c000
	v_add_u32_e32 v174, s88, v155
	v_add_u32_e32 v190, s89, v155
	ds_read_b128 v[148:151], v174
	ds_read_b128 v[158:161], v174 offset:1024
	ds_read_b128 v[162:165], v174 offset:2048
	ds_read_b128 v[174:177], v174 offset:3072
	ds_read_b128 v[178:181], v190
	ds_read_b128 v[182:185], v190 offset:1024
	ds_read_b128 v[186:189], v190 offset:2048
	ds_read_b128 v[190:193], v190 offset:3072
	ds_read_b128 v[194:197], v157 offset:32768
	ds_read_b128 v[198:201], v157 offset:33792
	ds_read_b128 v[202:205], v157 offset:34816
	ds_read_b128 v[206:209], v157 offset:35840
	ds_read_b128 v[210:213], v157 offset:36864
	ds_read_b128 v[214:217], v157 offset:37888
	ds_read_b128 v[218:221], v157 offset:38912
	ds_read_b128 v[222:225], v157 offset:39936
	s_waitcnt vmcnt(8)
	s_waitcnt lgkmcnt(0)
	s_barrier
	s_setprio 1
	s_waitcnt lgkmcnt(0)
	v_mfma_f32_16x16x32_bf16 v[126:129], v[148:151], v[194:197], v[126:129]
	v_mfma_f32_16x16x32_bf16 v[122:125], v[162:165], v[194:197], v[122:125]
	v_mfma_f32_16x16x32_bf16 v[110:113], v[148:151], v[202:205], v[110:113]
	v_mfma_f32_16x16x32_bf16 v[106:109], v[162:165], v[202:205], v[106:109]
	v_mfma_f32_16x16x32_bf16 v[94:97], v[148:151], v[210:213], v[94:97]
	v_mfma_f32_16x16x32_bf16 v[90:93], v[162:165], v[210:213], v[90:93]
	v_mfma_f32_16x16x32_bf16 v[78:81], v[148:151], v[218:221], v[78:81]
	v_mfma_f32_16x16x32_bf16 v[74:77], v[162:165], v[218:221], v[74:77]
	v_mfma_f32_16x16x32_bf16 v[126:129], v[158:161], v[198:201], v[126:129]
	v_mfma_f32_16x16x32_bf16 v[122:125], v[174:177], v[198:201], v[122:125]
	v_mfma_f32_16x16x32_bf16 v[110:113], v[158:161], v[206:209], v[110:113]
	v_mfma_f32_16x16x32_bf16 v[106:109], v[174:177], v[206:209], v[106:109]
	v_mfma_f32_16x16x32_bf16 v[94:97], v[158:161], v[214:217], v[94:97]
	v_mfma_f32_16x16x32_bf16 v[90:93], v[174:177], v[214:217], v[90:93]
	v_mfma_f32_16x16x32_bf16 v[78:81], v[158:161], v[222:225], v[78:81]
	v_mfma_f32_16x16x32_bf16 v[74:77], v[174:177], v[222:225], v[74:77]
	s_setprio 0
	s_setprio 1
	v_mfma_f32_16x16x32_bf16 v[118:121], v[178:181], v[194:197], v[118:121]
	v_mfma_f32_16x16x32_bf16 v[114:117], v[186:189], v[194:197], v[114:117]
	v_mfma_f32_16x16x32_bf16 v[102:105], v[178:181], v[202:205], v[102:105]
	v_mfma_f32_16x16x32_bf16 v[98:101], v[186:189], v[202:205], v[98:101]
	v_mfma_f32_16x16x32_bf16 v[86:89], v[178:181], v[210:213], v[86:89]
	v_mfma_f32_16x16x32_bf16 v[82:85], v[186:189], v[210:213], v[82:85]
	v_mfma_f32_16x16x32_bf16 v[70:73], v[178:181], v[218:221], v[70:73]
	v_mfma_f32_16x16x32_bf16 v[66:69], v[186:189], v[218:221], v[66:69]
	v_mfma_f32_16x16x32_bf16 v[118:121], v[182:185], v[198:201], v[118:121]
	v_mfma_f32_16x16x32_bf16 v[114:117], v[190:193], v[198:201], v[114:117]
	v_mfma_f32_16x16x32_bf16 v[102:105], v[182:185], v[206:209], v[102:105]
	v_mfma_f32_16x16x32_bf16 v[98:101], v[190:193], v[206:209], v[98:101]
	v_mfma_f32_16x16x32_bf16 v[86:89], v[182:185], v[214:217], v[86:89]
	v_mfma_f32_16x16x32_bf16 v[82:85], v[190:193], v[214:217], v[82:85]
	v_mfma_f32_16x16x32_bf16 v[70:73], v[182:185], v[222:225], v[70:73]
	v_mfma_f32_16x16x32_bf16 v[66:69], v[190:193], v[222:225], v[66:69]
	s_setprio 0
	s_barrier
; #define PG8_STAGE(bufoff, gbase, voff) do { _Pragma("unroll") for (int _i = 0; _i < 2; ++_i) \
;         __builtin_amdgcn_global_load_lds((const unsigned*)((const char*)(gbase) + (voff)[_i]), (LAS unsigned*)(lds + (bufoff) + ldsw + _i * 8192), 16, 0, 0); } while (0)
; #define PG8_LDA(dst, b, h) do { _Pragma("unroll") for (int m = 0; m < 4; ++m) _Pragma("unroll") for (int k = 0; k < 2; ++k) dst[m][k] = *(const LAS bf16x8*)(lds + PG8_SA(b, h) + aoff + m * 2048 + k * 1024); } while (0)
; #define PG8_MMA(ai, bj, At, Bt) do { __builtin_amdgcn_s_setprio(1); _Pragma("unroll") for (int m = 0; m < 4; ++m) _Pragma("unroll") for (int n = 0; n < 2; ++n) _Pragma("unroll") for (int k = 0; k < 2; ++k) \
;         acc[ai][bj][m][n] = __builtin_amdgcn_mfma_f32_16x16x32_bf16(Bt[n][k], At[m][k], acc[ai][bj][m][n], 0, 0, 0); __builtin_amdgcn_s_setprio(0); } while (0)
; #define PG8_WAIT_V(n) asm volatile("s_waitcnt vmcnt(" #n ")" ::: "memory")
; #define PG8_WAIT_L(n) asm volatile("s_waitcnt lgkmcnt(" #n ")" ::: "memory")
; #define PG8_BAR __builtin_amdgcn_s_barrier()
; #define PG8_SCHED __builtin_amdgcn_sched_barrier(0)
; template <bool ALIGN_EPI, bool SP2, class Epi, class Sched>
; __device__ __forceinline__ void gemm_phase(LAS unsigned char* lds, const Gemm g, const Sched& S, const Epi& E) {
;     ...
;             PG8_STAGE(PG8_SB(1, 0), b3, voffB); PG8_STAGE(PG8_SB(1, 1), b3 + hstep, voffB); PG8_STAGE(PG8_SA(1, 0), a3, voffA); PG8_SCHED; PG8_LDA(At, 1, 1);
;             PG8_WAIT_V(8); PG8_WAIT_L(0); PG8_BAR; PG8_MMA(1, 0, At, B0); PG8_MMA(1, 1, At, B1); PG8_BAR; PG8_SCHED;
	s_add_i32 s88, s88, s61
	v_lshl_add_u64 v[152:153], v[152:153], 0, s[8:9]
	s_mov_b32 m0, s88
	s_nop 0
	global_load_lds_dwordx4 v[152:153], off
	v_lshl_add_u64 v[152:153], v[226:227], 0, s[8:9]
	s_add_i32 m0, s88, 0x2000
	s_add_i32 s88, s89, s61
	global_load_lds_dwordx4 v[152:153], off
	v_lshl_add_u64 v[152:153], v[228:229], 0, s[8:9]
	s_mov_b32 m0, s88
	s_nop 0
	global_load_lds_dwordx4 v[152:153], off
	v_lshl_add_u64 v[152:153], v[230:231], 0, s[8:9]
	s_add_i32 m0, s88, 0x2000
	s_nop 0
	global_load_lds_dwordx4 v[152:153], off
	v_lshl_add_u64 v[152:153], v[232:233], 0, s[8:9]
	s_mov_b32 m0, s67
	s_nop 0
	global_load_lds_dwordx4 v[152:153], off
	v_lshl_add_u64 v[152:153], v[234:235], 0, s[8:9]
	s_mov_b32 m0, s68
	s_nop 0
	global_load_lds_dwordx4 v[152:153], off
	ds_read_b128 v[194:197], v157 offset:49152
	ds_read_b128 v[198:201], v157 offset:50176
	ds_read_b128 v[202:205], v157 offset:51200
	ds_read_b128 v[206:209], v157 offset:52224
	ds_read_b128 v[210:213], v157 offset:53248
	ds_read_b128 v[214:217], v157 offset:54272
	ds_read_b128 v[218:221], v157 offset:55296
	ds_read_b128 v[222:225], v157 offset:56320
	s_waitcnt vmcnt(8)
	s_waitcnt lgkmcnt(0)
	s_barrier
	s_setprio 1
	s_waitcnt lgkmcnt(0)
	v_mfma_f32_16x16x32_bf16 v[62:65], v[148:151], v[194:197], v[62:65]
	v_mfma_f32_16x16x32_bf16 v[58:61], v[162:165], v[194:197], v[58:61]
	v_mfma_f32_16x16x32_bf16 v[46:49], v[148:151], v[202:205], v[46:49]
	v_mfma_f32_16x16x32_bf16 v[42:45], v[162:165], v[202:205], v[42:45]
	v_mfma_f32_16x16x32_bf16 v[30:33], v[148:151], v[210:213], v[30:33]
	v_mfma_f32_16x16x32_bf16 v[26:29], v[162:165], v[210:213], v[26:29]
	v_mfma_f32_16x16x32_bf16 v[14:17], v[148:151], v[218:221], v[14:17]
	v_mfma_f32_16x16x32_bf16 v[10:13], v[162:165], v[218:221], v[10:13]
	v_mfma_f32_16x16x32_bf16 v[62:65], v[158:161], v[198:201], v[62:65]
	v_mfma_f32_16x16x32_bf16 v[58:61], v[174:177], v[198:201], v[58:61]
	v_mfma_f32_16x16x32_bf16 v[46:49], v[158:161], v[206:209], v[46:49]
	v_mfma_f32_16x16x32_bf16 v[42:45], v[174:177], v[206:209], v[42:45]
	v_mfma_f32_16x16x32_bf16 v[30:33], v[158:161], v[214:217], v[30:33]
	v_mfma_f32_16x16x32_bf16 v[26:29], v[174:177], v[214:217], v[26:29]
	v_mfma_f32_16x16x32_bf16 v[14:17], v[158:161], v[222:225], v[14:17]
	v_mfma_f32_16x16x32_bf16 v[10:13], v[174:177], v[222:225], v[10:13]
	s_setprio 0
	s_setprio 1
	v_mfma_f32_16x16x32_bf16 v[54:57], v[178:181], v[194:197], v[54:57]
	v_mfma_f32_16x16x32_bf16 v[50:53], v[186:189], v[194:197], v[50:53]
	v_mfma_f32_16x16x32_bf16 v[38:41], v[178:181], v[202:205], v[38:41]
	v_mfma_f32_16x16x32_bf16 v[34:37], v[186:189], v[202:205], v[34:37]
	v_mfma_f32_16x16x32_bf16 v[22:25], v[178:181], v[210:213], v[22:25]
	v_mfma_f32_16x16x32_bf16 v[18:21], v[186:189], v[210:213], v[18:21]
	v_mfma_f32_16x16x32_bf16 v[6:9], v[178:181], v[218:221], v[6:9]
	v_mfma_f32_16x16x32_bf16 v[2:5], v[186:189], v[218:221], v[2:5]
	v_mfma_f32_16x16x32_bf16 v[54:57], v[182:185], v[198:201], v[54:57]
	v_mfma_f32_16x16x32_bf16 v[50:53], v[190:193], v[198:201], v[50:53]
	v_mfma_f32_16x16x32_bf16 v[38:41], v[182:185], v[206:209], v[38:41]
	v_mfma_f32_16x16x32_bf16 v[34:37], v[190:193], v[206:209], v[34:37]
	v_mfma_f32_16x16x32_bf16 v[22:25], v[182:185], v[214:217], v[22:25]
	v_mfma_f32_16x16x32_bf16 v[18:21], v[190:193], v[214:217], v[18:21]
	v_mfma_f32_16x16x32_bf16 v[6:9], v[182:185], v[222:225], v[6:9]
	v_mfma_f32_16x16x32_bf16 v[2:5], v[190:193], v[222:225], v[2:5]
	s_setprio 0
	s_barrier
	s_add_u32 s86, s86, 0x100
	s_addc_u32 s87, s87, 0
	s_add_u32 s24, s24, 0x100
	s_addc_u32 s71, s71, 0
	s_cmp_ge_i32 s90, s66
	s_mov_b32 s88, s90
	s_cbranch_scc0 .LBB0_619
	v_readlane_b32 s88, v240, 29
	v_readlane_b32 s94, v240, 31
	v_readlane_b32 s89, v240, 30
	v_readlane_b32 s95, v240, 32

; #define PG8_STAGE(bufoff, gbase, voff) do { _Pragma("unroll") for (int _i = 0; _i < 2; ++_i) \
;         __builtin_amdgcn_global_load_lds((const unsigned*)((const char*)(gbase) + (voff)[_i]), (LAS unsigned*)(lds + (bufoff) + ldsw + _i * 8192), 16, 0, 0); } while (0)
; #define PG8_LDA(dst, b, h) do { _Pragma("unroll") for (int m = 0; m < 4; ++m) _Pragma("unroll") for (int k = 0; k < 2; ++k) dst[m][k] = *(const LAS bf16x8*)(lds + PG8_SA(b, h) + aoff + m * 2048 + k * 1024); } while (0)
; #define PG8_LDB(dst, b, h) do { _Pragma("unroll") for (int n = 0; n < 2; ++n) _Pragma("unroll") for (int k = 0; k < 2; ++k) dst[n][k] = *(const LAS bf16x8*)(lds + PG8_SB(b, h) + boff + n * 2048 + k * 1024); } while (0)
; #define PG8_SCHED __builtin_amdgcn_sched_barrier(0)
;     __device__ __forceinline__ bool zero_after(const Unit& u) const { return (u.pm >> 6) == 3; }
; template <bool ALIGN_EPI, bool SP2, class Epi, class Sched>
; __device__ __forceinline__ void gemm_phase(LAS unsigned char* lds, const Gemm g, const Sched& S, const Epi& E) {
;     ...
;         for (int t = 0; t < nt; t += 2) {
;             const bool last = (t == nt - 2);
;             const char* a1 = cA + (size_t)(t + 1) * kstep;
;             const char* a2 = last ? nA : cA + (size_t)(t + 2) * kstep; const char* b2 = last ? nB : cB + (size_t)(t + 2) * kstep;
;             const char* a3 = a2 + kstep; const char* b3 = b2 + kstep;
;             if constexpr (SP2) {
;             PG8_STAGE(PG8_SA(1, 1), a1 + hstep, voffA); PG8_SCHED; PG8_LDB(B0, 0, 0); PG8_LDB(B1, 0, 1); PG8_SCHED; PG8_LDA(At, 0, 0);
;     ...
;         if (E.zero_after(cur))
; #pragma unroll
;         for (int a = 0; a < 2; ++a)
; #pragma unroll
;             for (int b = 0; b < 2; ++b)
; #pragma unroll
;                 for (int m = 0; m < 4; ++m)
; #pragma unroll
;                     for (int n = 0; n < 2; ++n) acc[a][b][m][n] = (f32x4){0.f, 0.f, 0.f, 0.f};
.LBB0_833:
	v_mov_b32_e32 v129, 0
	s_andn2_b64 vcc, exec, s[44:45]
	v_mov_b32_e32 v128, v129
	v_mov_b32_e32 v127, v129
	v_mov_b32_e32 v126, v129
	v_mov_b32_e32 v125, v129
	v_mov_b32_e32 v124, v129
	v_mov_b32_e32 v123, v129
	v_mov_b32_e32 v122, v129
	v_mov_b32_e32 v113, v129
	v_mov_b32_e32 v112, v129
	v_mov_b32_e32 v111, v129
	v_mov_b32_e32 v110, v129
	v_mov_b32_e32 v109, v129
	v_mov_b32_e32 v108, v129
	v_mov_b32_e32 v107, v129
	v_mov_b32_e32 v106, v129
	v_mov_b32_e32 v97, v129
	v_mov_b32_e32 v96, v129
	v_mov_b32_e32 v95, v129
	v_mov_b32_e32 v94, v129
	v_mov_b32_e32 v93, v129
	v_mov_b32_e32 v92, v129
	v_mov_b32_e32 v91, v129
	v_mov_b32_e32 v90, v129
	v_mov_b32_e32 v81, v129
	v_mov_b32_e32 v80, v129
	v_mov_b32_e32 v79, v129
	v_mov_b32_e32 v78, v129
	v_mov_b32_e32 v77, v129
	v_mov_b32_e32 v76, v129
	v_mov_b32_e32 v75, v129
	v_mov_b32_e32 v74, v129
	v_mov_b32_e32 v121, v129
	v_mov_b32_e32 v120, v129
	v_mov_b32_e32 v119, v129
	v_mov_b32_e32 v118, v129
	v_mov_b32_e32 v117, v129
	v_mov_b32_e32 v116, v129
	v_mov_b32_e32 v115, v129
	v_mov_b32_e32 v114, v129
	v_mov_b32_e32 v105, v129
	v_mov_b32_e32 v104, v129
	v_mov_b32_e32 v103, v129
	v_mov_b32_e32 v102, v129
	v_mov_b32_e32 v101, v129
	v_mov_b32_e32 v100, v129
	v_mov_b32_e32 v99, v129
	v_mov_b32_e32 v98, v129
	v_mov_b32_e32 v89, v129
	v_mov_b32_e32 v88, v129
	v_mov_b32_e32 v87, v129
	v_mov_b32_e32 v86, v129
	v_mov_b32_e32 v85, v129
	v_mov_b32_e32 v84, v129
	v_mov_b32_e32 v83, v129
	v_mov_b32_e32 v82, v129
	v_mov_b32_e32 v73, v129
	v_mov_b32_e32 v72, v129
	v_mov_b32_e32 v71, v129
	v_mov_b32_e32 v70, v129
	v_mov_b32_e32 v69, v129
	v_mov_b32_e32 v68, v129
	v_mov_b32_e32 v67, v129
	v_mov_b32_e32 v66, v129
	v_mov_b32_e32 v65, v129
	v_mov_b32_e32 v64, v129
	v_mov_b32_e32 v63, v129
	v_mov_b32_e32 v62, v129
	v_mov_b32_e32 v61, v129
	v_mov_b32_e32 v60, v129
	v_mov_b32_e32 v59, v129
	v_mov_b32_e32 v58, v129
	v_mov_b32_e32 v49, v129
	v_mov_b32_e32 v48, v129
	v_mov_b32_e32 v47, v129
	v_mov_b32_e32 v46, v129
	v_mov_b32_e32 v45, v129
	v_mov_b32_e32 v44, v129
	v_mov_b32_e32 v43, v129
	v_mov_b32_e32 v42, v129
	v_mov_b32_e32 v33, v129
	v_mov_b32_e32 v32, v129
	v_mov_b32_e32 v31, v129
	v_mov_b32_e32 v30, v129
	v_mov_b32_e32 v29, v129
	v_mov_b32_e32 v28, v129
	v_mov_b32_e32 v27, v129
	v_mov_b32_e32 v26, v129
	v_mov_b32_e32 v17, v129
	v_mov_b32_e32 v16, v129
	v_mov_b32_e32 v15, v129
	v_mov_b32_e32 v14, v129
	v_mov_b32_e32 v13, v129
	v_mov_b32_e32 v12, v129
	v_mov_b32_e32 v11, v129
	v_mov_b32_e32 v10, v129
	v_mov_b32_e32 v57, v129
	v_mov_b32_e32 v56, v129
	v_mov_b32_e32 v55, v129
	v_mov_b32_e32 v54, v129
	v_mov_b32_e32 v53, v129
	v_mov_b32_e32 v52, v129
	v_mov_b32_e32 v51, v129
	v_mov_b32_e32 v50, v129
	v_mov_b32_e32 v41, v129
	v_mov_b32_e32 v40, v129
	v_mov_b32_e32 v39, v129
	v_mov_b32_e32 v38, v129
	v_mov_b32_e32 v37, v129
	v_mov_b32_e32 v36, v129
	v_mov_b32_e32 v35, v129
	v_mov_b32_e32 v34, v129
	v_mov_b32_e32 v25, v129
	v_mov_b32_e32 v24, v129
	v_mov_b32_e32 v23, v129
	v_mov_b32_e32 v22, v129
	v_mov_b32_e32 v21, v129
	v_mov_b32_e32 v20, v129
	v_mov_b32_e32 v19, v129
	v_mov_b32_e32 v18, v129
	v_mov_b32_e32 v9, v129
	v_mov_b32_e32 v8, v129
	v_mov_b32_e32 v7, v129
	v_mov_b32_e32 v6, v129
	v_mov_b32_e32 v5, v129
	v_mov_b32_e32 v4, v129
	v_mov_b32_e32 v3, v129
	v_mov_b32_e32 v2, v129
	s_cbranch_vccnz .LBB0_836
	s_add_u32 s86, s86, 0x80
	s_addc_u32 s87, s87, 0
	s_add_u32 s24, s90, 0x100
	v_mov_b32_e32 v2, 0
	s_addc_u32 s90, s91, 0
	s_mov_b32 s88, 0
.LBB0_835:
	s_add_i32 s91, s88, 2
	s_add_u32 s74, s86, 0x80
	s_addc_u32 s75, s87, 0
	s_add_i32 m0, s62, 0xc000
	s_add_i32 s89, s62, 0xe000
	v_lshl_add_u64 v[136:137], s[86:87], 0, v[132:133]
	global_load_lds_dwordx4 v[136:137], off
	v_lshl_add_u64 v[136:137], s[86:87], 0, v[134:135]
	s_mov_b32 m0, s89
	s_cmp_eq_u32 s69, s88
	global_load_lds_dwordx4 v[136:137], off
	s_cselect_b32 s88, s42, s74
	s_cselect_b32 s89, s43, s75
	s_cselect_b32 s97, s49, s90
	s_cselect_b32 s96, s48, s24
	s_add_i32 s74, 0, 0x10000
	v_add_u32_e32 v148, s74, v151
	s_add_i32 s75, 0, 0x14000
	ds_read_b128 v[136:139], v148
	ds_read_b128 v[154:157], v148 offset:1024
	ds_read_b128 v[158:161], v148 offset:2048
	ds_read_b128 v[162:165], v148 offset:3072
	v_add_u32_e32 v148, s75, v151
	ds_read_b128 v[174:177], v148
	ds_read_b128 v[178:181], v148 offset:1024
	ds_read_b128 v[182:185], v148 offset:2048
	ds_read_b128 v[186:189], v148 offset:3072
	ds_read_b128 v[190:193], v153
	ds_read_b128 v[194:197], v153 offset:1024
	ds_read_b128 v[198:201], v153 offset:2048
	ds_read_b128 v[202:205], v153 offset:3072
	ds_read_b128 v[206:209], v153 offset:4096
	ds_read_b128 v[210:213], v153 offset:5120
	ds_read_b128 v[214:217], v153 offset:6144
	ds_read_b128 v[218:221], v153 offset:7168
	s_waitcnt vmcnt(8)
	s_waitcnt lgkmcnt(0)
	s_barrier
; #define PG8_STAGE(bufoff, gbase, voff) do { _Pragma("unroll") for (int _i = 0; _i < 2; ++_i) \
;         __builtin_amdgcn_global_load_lds((const unsigned*)((const char*)(gbase) + (voff)[_i]), (LAS unsigned*)(lds + (bufoff) + ldsw + _i * 8192), 16, 0, 0); } while (0)
; #define PG8_LDA(dst, b, h) do { _Pragma("unroll") for (int m = 0; m < 4; ++m) _Pragma("unroll") for (int k = 0; k < 2; ++k) dst[m][k] = *(const LAS bf16x8*)(lds + PG8_SA(b, h) + aoff + m * 2048 + k * 1024); } while (0)
; #define PG8_MMA(ai, bj, At, Bt) do { __builtin_amdgcn_s_setprio(1); _Pragma("unroll") for (int m = 0; m < 4; ++m) _Pragma("unroll") for (int n = 0; n < 2; ++n) _Pragma("unroll") for (int k = 0; k < 2; ++k) \
;         acc[ai][bj][m][n] = __builtin_amdgcn_mfma_f32_16x16x32_bf16(Bt[n][k], At[m][k], acc[ai][bj][m][n], 0, 0, 0); __builtin_amdgcn_s_setprio(0); } while (0)
; #define PG8_WAIT_V(n) asm volatile("s_waitcnt vmcnt(" #n ")" ::: "memory")
; #define PG8_WAIT_L(n) asm volatile("s_waitcnt lgkmcnt(" #n ")" ::: "memory")
; #define PG8_BAR __builtin_amdgcn_s_barrier()
; #define PG8_SCHED __builtin_amdgcn_sched_barrier(0)
; template <bool ALIGN_EPI, bool SP2, class Epi, class Sched>
; __device__ __forceinline__ void gemm_phase(LAS unsigned char* lds, const Gemm g, const Sched& S, const Epi& E) {
;     ...
;             PG8_WAIT_V(8); PG8_WAIT_L(0); PG8_BAR; PG8_MMA(0, 0, At, B0); PG8_MMA(0, 1, At, B1); PG8_BAR; PG8_SCHED;
;             PG8_STAGE(PG8_SB(0, 0), b2, voffB); PG8_STAGE(PG8_SB(0, 1), b2 + hstep, voffB); PG8_STAGE(PG8_SA(0, 0), a2, voffA); PG8_SCHED; PG8_LDA(At, 0, 1);
;             PG8_WAIT_V(8); PG8_WAIT_L(0); PG8_BAR; PG8_MMA(1, 0, At, B0); PG8_MMA(1, 1, At, B1); PG8_BAR; PG8_SCHED;
	s_setprio 1
	s_waitcnt lgkmcnt(0)
	v_mfma_f32_16x16x32_bf16 v[126:129], v[136:139], v[190:193], v[126:129]
	v_mfma_f32_16x16x32_bf16 v[122:125], v[158:161], v[190:193], v[122:125]
	v_mfma_f32_16x16x32_bf16 v[110:113], v[136:139], v[198:201], v[110:113]
	v_mfma_f32_16x16x32_bf16 v[106:109], v[158:161], v[198:201], v[106:109]
	v_mfma_f32_16x16x32_bf16 v[94:97], v[136:139], v[206:209], v[94:97]
	v_mfma_f32_16x16x32_bf16 v[90:93], v[158:161], v[206:209], v[90:93]
	v_mfma_f32_16x16x32_bf16 v[78:81], v[136:139], v[214:217], v[78:81]
	v_mfma_f32_16x16x32_bf16 v[74:77], v[158:161], v[214:217], v[74:77]
	v_mfma_f32_16x16x32_bf16 v[126:129], v[154:157], v[194:197], v[126:129]
	v_mfma_f32_16x16x32_bf16 v[122:125], v[162:165], v[194:197], v[122:125]
	v_mfma_f32_16x16x32_bf16 v[110:113], v[154:157], v[202:205], v[110:113]
	v_mfma_f32_16x16x32_bf16 v[106:109], v[162:165], v[202:205], v[106:109]
	v_mfma_f32_16x16x32_bf16 v[94:97], v[154:157], v[210:213], v[94:97]
	v_mfma_f32_16x16x32_bf16 v[90:93], v[162:165], v[210:213], v[90:93]
	v_mfma_f32_16x16x32_bf16 v[78:81], v[154:157], v[218:221], v[78:81]
	v_mfma_f32_16x16x32_bf16 v[74:77], v[162:165], v[218:221], v[74:77]
	s_setprio 0
	s_setprio 1
	v_mfma_f32_16x16x32_bf16 v[118:121], v[174:177], v[190:193], v[118:121]
	v_mfma_f32_16x16x32_bf16 v[114:117], v[182:185], v[190:193], v[114:117]
	v_mfma_f32_16x16x32_bf16 v[102:105], v[174:177], v[198:201], v[102:105]
	v_mfma_f32_16x16x32_bf16 v[98:101], v[182:185], v[198:201], v[98:101]
	v_mfma_f32_16x16x32_bf16 v[86:89], v[174:177], v[206:209], v[86:89]
	v_mfma_f32_16x16x32_bf16 v[82:85], v[182:185], v[206:209], v[82:85]
	v_mfma_f32_16x16x32_bf16 v[70:73], v[174:177], v[214:217], v[70:73]
	v_mfma_f32_16x16x32_bf16 v[66:69], v[182:185], v[214:217], v[66:69]
	v_mfma_f32_16x16x32_bf16 v[118:121], v[178:181], v[194:197], v[118:121]
	v_mfma_f32_16x16x32_bf16 v[114:117], v[186:189], v[194:197], v[114:117]
	v_mfma_f32_16x16x32_bf16 v[102:105], v[178:181], v[202:205], v[102:105]
	v_mfma_f32_16x16x32_bf16 v[98:101], v[186:189], v[202:205], v[98:101]
	v_mfma_f32_16x16x32_bf16 v[86:89], v[178:181], v[210:213], v[86:89]
	v_mfma_f32_16x16x32_bf16 v[82:85], v[186:189], v[210:213], v[82:85]
	v_mfma_f32_16x16x32_bf16 v[70:73], v[178:181], v[218:221], v[70:73]
	v_mfma_f32_16x16x32_bf16 v[66:69], v[186:189], v[218:221], v[66:69]
	s_setprio 0
	s_barrier
	s_add_i32 s74, s74, s61
	v_lshl_add_u64 v[148:149], s[96:97], 0, v[0:1]
	s_mov_b32 m0, s74
	v_lshl_add_u64 v[222:223], s[96:97], 0, v[130:131]
	global_load_lds_dwordx4 v[148:149], off
	s_add_i32 m0, s74, 0x2000
	s_add_u32 s96, s96, s14
	s_addc_u32 s97, s97, s15
	s_add_i32 s74, s75, s61
	global_load_lds_dwordx4 v[222:223], off
	v_lshl_add_u64 v[224:225], s[96:97], 0, v[0:1]
	s_mov_b32 m0, s74
	v_lshl_add_u64 v[226:227], s[96:97], 0, v[130:131]
	global_load_lds_dwordx4 v[224:225], off
	s_add_i32 m0, s74, 0x2000
	v_lshl_add_u64 v[228:229], s[88:89], 0, v[0:1]
	global_load_lds_dwordx4 v[226:227], off
	s_mov_b32 m0, s62
	v_lshl_add_u64 v[230:231], s[88:89], 0, v[130:131]
	global_load_lds_dwordx4 v[228:229], off
	s_mov_b32 m0, s63
	s_nop 0
	global_load_lds_dwordx4 v[230:231], off
	ds_read_b128 v[190:193], v153 offset:16384
	ds_read_b128 v[194:197], v153 offset:17408
	ds_read_b128 v[198:201], v153 offset:18432
	ds_read_b128 v[202:205], v153 offset:19456
	ds_read_b128 v[206:209], v153 offset:20480
	ds_read_b128 v[210:213], v153 offset:21504
	ds_read_b128 v[214:217], v153 offset:22528
	ds_read_b128 v[218:221], v153 offset:23552
	s_waitcnt vmcnt(8)
	s_waitcnt lgkmcnt(0)
	s_barrier
	s_setprio 1
	s_waitcnt lgkmcnt(0)
	v_mfma_f32_16x16x32_bf16 v[62:65], v[136:139], v[190:193], v[62:65]
	v_mfma_f32_16x16x32_bf16 v[58:61], v[158:161], v[190:193], v[58:61]
	v_mfma_f32_16x16x32_bf16 v[46:49], v[136:139], v[198:201], v[46:49]
	v_mfma_f32_16x16x32_bf16 v[42:45], v[158:161], v[198:201], v[42:45]
	v_mfma_f32_16x16x32_bf16 v[30:33], v[136:139], v[206:209], v[30:33]
	v_mfma_f32_16x16x32_bf16 v[26:29], v[158:161], v[206:209], v[26:29]
	v_mfma_f32_16x16x32_bf16 v[14:17], v[136:139], v[214:217], v[14:17]
	v_mfma_f32_16x16x32_bf16 v[10:13], v[158:161], v[214:217], v[10:13]
	v_mfma_f32_16x16x32_bf16 v[62:65], v[154:157], v[194:197], v[62:65]
	v_mfma_f32_16x16x32_bf16 v[58:61], v[162:165], v[194:197], v[58:61]
	v_mfma_f32_16x16x32_bf16 v[46:49], v[154:157], v[202:205], v[46:49]
	v_mfma_f32_16x16x32_bf16 v[42:45], v[162:165], v[202:205], v[42:45]
	v_mfma_f32_16x16x32_bf16 v[30:33], v[154:157], v[210:213], v[30:33]
	v_mfma_f32_16x16x32_bf16 v[26:29], v[162:165], v[210:213], v[26:29]
	v_mfma_f32_16x16x32_bf16 v[14:17], v[154:157], v[218:221], v[14:17]
	v_mfma_f32_16x16x32_bf16 v[10:13], v[162:165], v[218:221], v[10:13]
	s_setprio 0
	s_setprio 1
	v_mfma_f32_16x16x32_bf16 v[54:57], v[174:177], v[190:193], v[54:57]
	v_mfma_f32_16x16x32_bf16 v[50:53], v[182:185], v[190:193], v[50:53]
	v_mfma_f32_16x16x32_bf16 v[38:41], v[174:177], v[198:201], v[38:41]
	v_mfma_f32_16x16x32_bf16 v[34:37], v[182:185], v[198:201], v[34:37]
	v_mfma_f32_16x16x32_bf16 v[22:25], v[174:177], v[206:209], v[22:25]
	v_mfma_f32_16x16x32_bf16 v[18:21], v[182:185], v[206:209], v[18:21]
	v_mfma_f32_16x16x32_bf16 v[6:9], v[174:177], v[214:217], v[6:9]
	v_mfma_f32_16x16x32_bf16 v[2:5], v[182:185], v[214:217], v[2:5]
	v_mfma_f32_16x16x32_bf16 v[54:57], v[178:181], v[194:197], v[54:57]
	v_mfma_f32_16x16x32_bf16 v[50:53], v[186:189], v[194:197], v[50:53]
	v_mfma_f32_16x16x32_bf16 v[38:41], v[178:181], v[202:205], v[38:41]
	v_mfma_f32_16x16x32_bf16 v[34:37], v[186:189], v[202:205], v[34:37]
	v_mfma_f32_16x16x32_bf16 v[22:25], v[178:181], v[210:213], v[22:25]
	v_mfma_f32_16x16x32_bf16 v[18:21], v[186:189], v[210:213], v[18:21]
	v_mfma_f32_16x16x32_bf16 v[6:9], v[178:181], v[218:221], v[6:9]
	v_mfma_f32_16x16x32_bf16 v[2:5], v[186:189], v[218:221], v[2:5]
	s_setprio 0
	s_barrier
; #define PG8_STAGE(bufoff, gbase, voff) do { _Pragma("unroll") for (int _i = 0; _i < 2; ++_i) \
;         __builtin_amdgcn_global_load_lds((const unsigned*)((const char*)(gbase) + (voff)[_i]), (LAS unsigned*)(lds + (bufoff) + ldsw + _i * 8192), 16, 0, 0); } while (0)
; #define PG8_LDA(dst, b, h) do { _Pragma("unroll") for (int m = 0; m < 4; ++m) _Pragma("unroll") for (int k = 0; k < 2; ++k) dst[m][k] = *(const LAS bf16x8*)(lds + PG8_SA(b, h) + aoff + m * 2048 + k * 1024); } while (0)
; #define PG8_LDB(dst, b, h) do { _Pragma("unroll") for (int n = 0; n < 2; ++n) _Pragma("unroll") for (int k = 0; k < 2; ++k) dst[n][k] = *(const LAS bf16x8*)(lds + PG8_SB(b, h) + boff + n * 2048 + k * 1024); } while (0)
; #define PG8_MMA(ai, bj, At, Bt) do { __builtin_amdgcn_s_setprio(1); _Pragma("unroll") for (int m = 0; m < 4; ++m) _Pragma("unroll") for (int n = 0; n < 2; ++n) _Pragma("unroll") for (int k = 0; k < 2; ++k) \
;         acc[ai][bj][m][n] = __builtin_amdgcn_mfma_f32_16x16x32_bf16(Bt[n][k], At[m][k], acc[ai][bj][m][n], 0, 0, 0); __builtin_amdgcn_s_setprio(0); } while (0)
; #define PG8_WAIT_V(n) asm volatile("s_waitcnt vmcnt(" #n ")" ::: "memory")
; #define PG8_WAIT_L(n) asm volatile("s_waitcnt lgkmcnt(" #n ")" ::: "memory")
; #define PG8_BAR __builtin_amdgcn_s_barrier()
; #define PG8_SCHED __builtin_amdgcn_sched_barrier(0)
; template <bool ALIGN_EPI, bool SP2, class Epi, class Sched>
; __device__ __forceinline__ void gemm_phase(LAS unsigned char* lds, const Gemm g, const Sched& S, const Epi& E) {
;     ...
;             PG8_STAGE(PG8_SA(0, 1), a2 + hstep, voffA); PG8_SCHED; PG8_LDB(B0, 1, 0); PG8_LDB(B1, 1, 1); PG8_SCHED; PG8_LDA(At, 1, 0);
;             PG8_WAIT_V(8); PG8_WAIT_L(0); PG8_BAR; PG8_MMA(0, 0, At, B0); PG8_MMA(0, 1, At, B1); PG8_BAR; PG8_SCHED;
	s_add_u32 s88, s88, s14
	s_addc_u32 s89, s89, s15
	s_mov_b32 m0, s64
	v_lshl_add_u64 v[136:137], s[88:89], 0, v[0:1]
	global_load_lds_dwordx4 v[136:137], off
	v_lshl_add_u64 v[136:137], s[88:89], 0, v[130:131]
	s_mov_b32 m0, s65
	s_nop 0
	global_load_lds_dwordx4 v[136:137], off
	s_add_i32 s74, 0, 0x18000
	s_add_i32 s75, 0, 0x1c000
	v_add_u32_e32 v162, s74, v151
	v_add_u32_e32 v186, s75, v151
	ds_read_b128 v[136:139], v162
	ds_read_b128 v[154:157], v162 offset:1024
	ds_read_b128 v[158:161], v162 offset:2048
	ds_read_b128 v[162:165], v162 offset:3072
	ds_read_b128 v[174:177], v186
	ds_read_b128 v[178:181], v186 offset:1024
	ds_read_b128 v[182:185], v186 offset:2048
	ds_read_b128 v[186:189], v186 offset:3072
	ds_read_b128 v[190:193], v153 offset:32768
	ds_read_b128 v[194:197], v153 offset:33792
	ds_read_b128 v[198:201], v153 offset:34816
	ds_read_b128 v[202:205], v153 offset:35840
	ds_read_b128 v[206:209], v153 offset:36864
	ds_read_b128 v[210:213], v153 offset:37888
	ds_read_b128 v[214:217], v153 offset:38912
	ds_read_b128 v[218:221], v153 offset:39936
	s_waitcnt vmcnt(8)
	s_waitcnt lgkmcnt(0)
	s_barrier
	s_setprio 1
	s_waitcnt lgkmcnt(0)
	v_mfma_f32_16x16x32_bf16 v[126:129], v[136:139], v[190:193], v[126:129]
	v_mfma_f32_16x16x32_bf16 v[122:125], v[158:161], v[190:193], v[122:125]
	v_mfma_f32_16x16x32_bf16 v[110:113], v[136:139], v[198:201], v[110:113]
	v_mfma_f32_16x16x32_bf16 v[106:109], v[158:161], v[198:201], v[106:109]
	v_mfma_f32_16x16x32_bf16 v[94:97], v[136:139], v[206:209], v[94:97]
	v_mfma_f32_16x16x32_bf16 v[90:93], v[158:161], v[206:209], v[90:93]
	v_mfma_f32_16x16x32_bf16 v[78:81], v[136:139], v[214:217], v[78:81]
	v_mfma_f32_16x16x32_bf16 v[74:77], v[158:161], v[214:217], v[74:77]
	v_mfma_f32_16x16x32_bf16 v[126:129], v[154:157], v[194:197], v[126:129]
	v_mfma_f32_16x16x32_bf16 v[122:125], v[162:165], v[194:197], v[122:125]
	v_mfma_f32_16x16x32_bf16 v[110:113], v[154:157], v[202:205], v[110:113]
	v_mfma_f32_16x16x32_bf16 v[106:109], v[162:165], v[202:205], v[106:109]
	v_mfma_f32_16x16x32_bf16 v[94:97], v[154:157], v[210:213], v[94:97]
	v_mfma_f32_16x16x32_bf16 v[90:93], v[162:165], v[210:213], v[90:93]
	v_mfma_f32_16x16x32_bf16 v[78:81], v[154:157], v[218:221], v[78:81]
	v_mfma_f32_16x16x32_bf16 v[74:77], v[162:165], v[218:221], v[74:77]
	s_setprio 0
	s_setprio 1
	v_mfma_f32_16x16x32_bf16 v[118:121], v[174:177], v[190:193], v[118:121]
	v_mfma_f32_16x16x32_bf16 v[114:117], v[182:185], v[190:193], v[114:117]
	v_mfma_f32_16x16x32_bf16 v[102:105], v[174:177], v[198:201], v[102:105]
	v_mfma_f32_16x16x32_bf16 v[98:101], v[182:185], v[198:201], v[98:101]
	v_mfma_f32_16x16x32_bf16 v[86:89], v[174:177], v[206:209], v[86:89]
	v_mfma_f32_16x16x32_bf16 v[82:85], v[182:185], v[206:209], v[82:85]
	v_mfma_f32_16x16x32_bf16 v[70:73], v[174:177], v[214:217], v[70:73]
	v_mfma_f32_16x16x32_bf16 v[66:69], v[182:185], v[214:217], v[66:69]
	v_mfma_f32_16x16x32_bf16 v[118:121], v[178:181], v[194:197], v[118:121]
	v_mfma_f32_16x16x32_bf16 v[114:117], v[186:189], v[194:197], v[114:117]
	v_mfma_f32_16x16x32_bf16 v[102:105], v[178:181], v[202:205], v[102:105]
	v_mfma_f32_16x16x32_bf16 v[98:101], v[186:189], v[202:205], v[98:101]
	v_mfma_f32_16x16x32_bf16 v[86:89], v[178:181], v[210:213], v[86:89]
	v_mfma_f32_16x16x32_bf16 v[82:85], v[186:189], v[210:213], v[82:85]
	v_mfma_f32_16x16x32_bf16 v[70:73], v[178:181], v[218:221], v[70:73]
	v_mfma_f32_16x16x32_bf16 v[66:69], v[186:189], v[218:221], v[66:69]
	s_setprio 0
	s_barrier
; #define PG8_STAGE(bufoff, gbase, voff) do { _Pragma("unroll") for (int _i = 0; _i < 2; ++_i) \
;         __builtin_amdgcn_global_load_lds((const unsigned*)((const char*)(gbase) + (voff)[_i]), (LAS unsigned*)(lds + (bufoff) + ldsw + _i * 8192), 16, 0, 0); } while (0)
; #define PG8_LDA(dst, b, h) do { _Pragma("unroll") for (int m = 0; m < 4; ++m) _Pragma("unroll") for (int k = 0; k < 2; ++k) dst[m][k] = *(const LAS bf16x8*)(lds + PG8_SA(b, h) + aoff + m * 2048 + k * 1024); } while (0)
; #define PG8_MMA(ai, bj, At, Bt) do { __builtin_amdgcn_s_setprio(1); _Pragma("unroll") for (int m = 0; m < 4; ++m) _Pragma("unroll") for (int n = 0; n < 2; ++n) _Pragma("unroll") for (int k = 0; k < 2; ++k) \
;         acc[ai][bj][m][n] = __builtin_amdgcn_mfma_f32_16x16x32_bf16(Bt[n][k], At[m][k], acc[ai][bj][m][n], 0, 0, 0); __builtin_amdgcn_s_setprio(0); } while (0)
; #define PG8_WAIT_V(n) asm volatile("s_waitcnt vmcnt(" #n ")" ::: "memory")
; #define PG8_WAIT_L(n) asm volatile("s_waitcnt lgkmcnt(" #n ")" ::: "memory")
; #define PG8_BAR __builtin_amdgcn_s_barrier()
; #define PG8_SCHED __builtin_amdgcn_sched_barrier(0)
; template <bool ALIGN_EPI, bool SP2, class Epi, class Sched>
; __device__ __forceinline__ void gemm_phase(LAS unsigned char* lds, const Gemm g, const Sched& S, const Epi& E) {
;     ...
;             PG8_STAGE(PG8_SB(1, 0), b3, voffB); PG8_STAGE(PG8_SB(1, 1), b3 + hstep, voffB); PG8_STAGE(PG8_SA(1, 0), a3, voffA); PG8_SCHED; PG8_LDA(At, 1, 1);
;             PG8_WAIT_V(8); PG8_WAIT_L(0); PG8_BAR; PG8_MMA(1, 0, At, B0); PG8_MMA(1, 1, At, B1); PG8_BAR; PG8_SCHED;
	s_add_i32 s74, s74, s61
	v_lshl_add_u64 v[148:149], v[148:149], 0, s[8:9]
	s_mov_b32 m0, s74
	s_nop 0
	global_load_lds_dwordx4 v[148:149], off
	v_lshl_add_u64 v[148:149], v[222:223], 0, s[8:9]
	s_add_i32 m0, s74, 0x2000
	s_add_i32 s74, s75, s61
	global_load_lds_dwordx4 v[148:149], off
	v_lshl_add_u64 v[148:149], v[224:225], 0, s[8:9]
	s_mov_b32 m0, s74
	s_nop 0
	global_load_lds_dwordx4 v[148:149], off
	v_lshl_add_u64 v[148:149], v[226:227], 0, s[8:9]
	s_add_i32 m0, s74, 0x2000
	s_nop 0
	global_load_lds_dwordx4 v[148:149], off
	v_lshl_add_u64 v[148:149], v[228:229], 0, s[8:9]
	s_mov_b32 m0, s67
	s_nop 0
	global_load_lds_dwordx4 v[148:149], off
	v_lshl_add_u64 v[148:149], v[230:231], 0, s[8:9]
	s_mov_b32 m0, s68
	s_nop 0
	global_load_lds_dwordx4 v[148:149], off
	ds_read_b128 v[190:193], v153 offset:49152
	ds_read_b128 v[194:197], v153 offset:50176
	ds_read_b128 v[198:201], v153 offset:51200
	ds_read_b128 v[202:205], v153 offset:52224
	ds_read_b128 v[206:209], v153 offset:53248
	ds_read_b128 v[210:213], v153 offset:54272
	ds_read_b128 v[214:217], v153 offset:55296
	ds_read_b128 v[218:221], v153 offset:56320
	s_waitcnt vmcnt(8)
	s_waitcnt lgkmcnt(0)
	s_barrier
	s_setprio 1
	s_waitcnt lgkmcnt(0)
	v_mfma_f32_16x16x32_bf16 v[62:65], v[136:139], v[190:193], v[62:65]
	v_mfma_f32_16x16x32_bf16 v[58:61], v[158:161], v[190:193], v[58:61]
	v_mfma_f32_16x16x32_bf16 v[46:49], v[136:139], v[198:201], v[46:49]
	v_mfma_f32_16x16x32_bf16 v[42:45], v[158:161], v[198:201], v[42:45]
	v_mfma_f32_16x16x32_bf16 v[30:33], v[136:139], v[206:209], v[30:33]
	v_mfma_f32_16x16x32_bf16 v[26:29], v[158:161], v[206:209], v[26:29]
	v_mfma_f32_16x16x32_bf16 v[14:17], v[136:139], v[214:217], v[14:17]
	v_mfma_f32_16x16x32_bf16 v[10:13], v[158:161], v[214:217], v[10:13]
	v_mfma_f32_16x16x32_bf16 v[62:65], v[154:157], v[194:197], v[62:65]
	v_mfma_f32_16x16x32_bf16 v[58:61], v[162:165], v[194:197], v[58:61]
	v_mfma_f32_16x16x32_bf16 v[46:49], v[154:157], v[202:205], v[46:49]
	v_mfma_f32_16x16x32_bf16 v[42:45], v[162:165], v[202:205], v[42:45]
	v_mfma_f32_16x16x32_bf16 v[30:33], v[154:157], v[210:213], v[30:33]
	v_mfma_f32_16x16x32_bf16 v[26:29], v[162:165], v[210:213], v[26:29]
	v_mfma_f32_16x16x32_bf16 v[14:17], v[154:157], v[218:221], v[14:17]
	v_mfma_f32_16x16x32_bf16 v[10:13], v[162:165], v[218:221], v[10:13]
	s_setprio 0
	s_setprio 1
	v_mfma_f32_16x16x32_bf16 v[54:57], v[174:177], v[190:193], v[54:57]
	v_mfma_f32_16x16x32_bf16 v[50:53], v[182:185], v[190:193], v[50:53]
	v_mfma_f32_16x16x32_bf16 v[38:41], v[174:177], v[198:201], v[38:41]
	v_mfma_f32_16x16x32_bf16 v[34:37], v[182:185], v[198:201], v[34:37]
	v_mfma_f32_16x16x32_bf16 v[22:25], v[174:177], v[206:209], v[22:25]
	v_mfma_f32_16x16x32_bf16 v[18:21], v[182:185], v[206:209], v[18:21]
	v_mfma_f32_16x16x32_bf16 v[6:9], v[174:177], v[214:217], v[6:9]
	v_mfma_f32_16x16x32_bf16 v[2:5], v[182:185], v[214:217], v[2:5]
	v_mfma_f32_16x16x32_bf16 v[54:57], v[178:181], v[194:197], v[54:57]
	v_mfma_f32_16x16x32_bf16 v[50:53], v[186:189], v[194:197], v[50:53]
	v_mfma_f32_16x16x32_bf16 v[38:41], v[178:181], v[202:205], v[38:41]
	v_mfma_f32_16x16x32_bf16 v[34:37], v[186:189], v[202:205], v[34:37]
	v_mfma_f32_16x16x32_bf16 v[22:25], v[178:181], v[210:213], v[22:25]
	v_mfma_f32_16x16x32_bf16 v[18:21], v[186:189], v[210:213], v[18:21]
	v_mfma_f32_16x16x32_bf16 v[6:9], v[178:181], v[218:221], v[6:9]
	v_mfma_f32_16x16x32_bf16 v[2:5], v[186:189], v[218:221], v[2:5]
	s_setprio 0
	s_barrier
	s_add_u32 s86, s86, 0x100
	s_addc_u32 s87, s87, 0
	s_add_u32 s24, s24, 0x100
	s_addc_u32 s90, s90, 0
	s_cmp_ge_i32 s91, s66
	s_mov_b32 s88, s91
	s_cbranch_scc0 .LBB0_835
